# agent-scope (sc1) loads for every consumer of a hand-off that no longer has an L1 invalidate (E_BR, RES4, RES6 operand/epilogue loads, E_BR gate loads, E_GU row stats)
# baseline (speedup 1.0000x reference)
.Lr6_nowait:
	s_waitcnt lgkmcnt(0)
	v_mad_i64_i32 v[0:1], s[16:17], s41, v218, v[96:97]
	s_and_b32 s16, s13, 7
	s_mul_i32 s30, s16, 0xb0000
	v_readfirstlane_b32 s16, v101
	s_mov_b32 m0, s16
	s_mov_b64 s[18:19], 0x400
	v_readfirstlane_b32 s16, v199
	global_load_lds_dwordx4 v[0:1], off sc1
	v_lshl_add_u64 v[4:5], v[0:1], 0, s[18:19]
	s_mov_b32 m0, s16
	v_readfirstlane_b32 s16, v200
	v_lshl_add_u64 v[2:3], v[98:99], 0, s[30:31]
	global_load_lds_dwordx4 v[4:5], off sc1
	s_mov_b32 m0, s16
	v_readfirstlane_b32 s16, v201
	global_load_lds_dwordx4 v[2:3], off sc1
	v_lshl_add_u64 v[4:5], v[2:3], 0, s[18:19]
	s_mov_b32 m0, s16
	v_readfirstlane_b32 s16, v202
	global_load_lds_dwordx4 v[4:5], off sc1
	v_lshl_add_u64 v[4:5], v[0:1], 0, s[44:45]
	s_mov_b32 m0, s16
	v_readfirstlane_b32 s16, v203
	global_load_lds_dwordx4 v[4:5], off sc1
	v_lshl_add_u64 v[4:5], v[0:1], 0, s[66:67]
	s_mov_b32 m0, s16
	v_readfirstlane_b32 s16, v204
	global_load_lds_dwordx4 v[4:5], off sc1
	v_lshl_add_u64 v[4:5], v[2:3], 0, s[44:45]
	s_mov_b32 m0, s16
	v_readfirstlane_b32 s16, v205
	global_load_lds_dwordx4 v[4:5], off sc1
	v_lshl_add_u64 v[4:5], v[2:3], 0, s[66:67]
	s_mov_b32 m0, s16
	v_readfirstlane_b32 s16, v206
	global_load_lds_dwordx4 v[4:5], off sc1
	v_lshl_add_u64 v[4:5], v[0:1], 0, s[28:29]
	s_mov_b32 m0, s16
	s_mov_b64 s[18:19], 0x4400
	v_readfirstlane_b32 s16, v207
	global_load_lds_dwordx4 v[4:5], off sc1
	v_lshl_add_u64 v[0:1], v[0:1], 0, s[18:19]
	s_mov_b32 m0, s16
	v_readfirstlane_b32 s16, v208
	global_load_lds_dwordx4 v[0:1], off sc1
	v_lshl_add_u64 v[0:1], v[2:3], 0, s[28:29]
	s_mov_b32 m0, s16
	v_readfirstlane_b32 s16, v209
	global_load_lds_dwordx4 v[0:1], off sc1
	v_lshl_add_u64 v[0:1], v[2:3], 0, s[18:19]
	s_mov_b32 m0, s16
	s_bfe_u32 s16, s38, 0x30007
	global_load_lds_dwordx4 v[0:1], off sc1
	v_mad_u64_u32 v[156:157], s[16:17], s16, v218, v[108:109]
	v_mad_i64_i32 v[158:159], s[16:17], s41, v218, v[110:111]
	s_lshl_b32 s16, s13, 7
	v_mov_b32_e32 v0, 0
	s_and_b32 s40, s16, 0x380
	s_mov_b32 s30, 0
	s_mov_b64 s[16:17], 0
	v_mov_b32_e32 v1, v0
	v_mov_b32_e32 v2, v0
	v_mov_b32_e32 v3, v0
	v_mov_b32_e32 v4, v0
	v_mov_b32_e32 v5, v0
	v_mov_b32_e32 v6, v0
	v_mov_b32_e32 v7, v0
	v_mov_b32_e32 v8, v0
	v_mov_b32_e32 v9, v0
	v_mov_b32_e32 v10, v0
	v_mov_b32_e32 v11, v0
	v_mov_b32_e32 v12, v0
	v_mov_b32_e32 v13, v0
	v_mov_b32_e32 v14, v0
	v_mov_b32_e32 v15, v0
	v_mov_b32_e32 v16, v0
	v_mov_b32_e32 v17, v0
	v_mov_b32_e32 v18, v0
	v_mov_b32_e32 v19, v0
	v_mov_b32_e32 v20, v0
	v_mov_b32_e32 v21, v0
	v_mov_b32_e32 v22, v0
	v_mov_b32_e32 v23, v0
	v_mov_b32_e32 v24, v0
	v_mov_b32_e32 v25, v0
	v_mov_b32_e32 v26, v0
	v_mov_b32_e32 v27, v0
	v_mov_b32_e32 v28, v0
	v_mov_b32_e32 v29, v0
	v_mov_b32_e32 v30, v0
	v_mov_b32_e32 v31, v0
	s_waitcnt vmcnt(0)
	v_mov_b32_e32 v32, v0
	v_mov_b32_e32 v33, v0
	v_mov_b32_e32 v34, v0
	v_mov_b32_e32 v35, v0
	v_mov_b32_e32 v36, v0
	v_mov_b32_e32 v37, v0
	v_mov_b32_e32 v38, v0
	v_mov_b32_e32 v39, v0
	v_mov_b32_e32 v40, v0
	v_mov_b32_e32 v41, v0
	v_mov_b32_e32 v42, v0
	v_mov_b32_e32 v43, v0
	v_mov_b32_e32 v44, v0
	v_mov_b32_e32 v45, v0
	v_mov_b32_e32 v46, v0
	v_mov_b32_e32 v47, v0
	v_mov_b32_e32 v48, v0
	v_mov_b32_e32 v49, v0
	v_mov_b32_e32 v50, v0
	v_mov_b32_e32 v51, v0
	v_mov_b32_e32 v52, v0
	v_mov_b32_e32 v53, v0
	v_mov_b32_e32 v54, v0
	v_mov_b32_e32 v55, v0
	v_mov_b32_e32 v56, v0
	v_mov_b32_e32 v57, v0
	v_mov_b32_e32 v58, v0
	v_mov_b32_e32 v59, v0
	v_mov_b32_e32 v60, v0
	v_mov_b32_e32 v61, v0
	v_mov_b32_e32 v62, v0
	v_mov_b32_e32 v63, v0
	s_branch .LBB0_32

.LBB0_32:
	s_waitcnt vmcnt(8)
	s_waitcnt lgkmcnt(0)
	s_barrier
	ds_read_b128 v[64:67], v210
	ds_read_b128 v[68:71], v210 offset:2048
	ds_read_b128 v[72:75], v211 offset:8192
	ds_read_b128 v[76:79], v211 offset:10240
	ds_read_b128 v[80:83], v227
	ds_read_b128 v[84:87], v227 offset:2048
	ds_read_b128 v[88:91], v228 offset:8192
	ds_read_b128 v[92:95], v228 offset:10240
	v_lshl_add_u64 v[160:161], v[156:157], 0, s[16:17]
	s_mov_b64 s[18:19], 0x8054000
	v_lshl_add_u64 v[164:165], v[160:161], 0, s[18:19]
	s_mov_b64 s[18:19], 0x8054400
	v_lshl_add_u64 v[166:167], v[160:161], 0, s[18:19]
	v_lshl_add_u64 v[162:163], v[158:159], 0, s[16:17]
	s_mov_b64 s[18:19], 0x16cd4000
	v_lshl_add_u64 v[168:169], v[162:163], 0, s[18:19]
	s_mov_b64 s[18:19], 0x16cd4400
	v_lshl_add_u64 v[170:171], v[162:163], 0, s[18:19]
	v_readfirstlane_b32 s18, v229
	s_mov_b32 m0, s18
	v_readfirstlane_b32 s18, v230
	global_load_lds_dwordx4 v[168:169], off sc1
	s_mov_b32 m0, s18
	v_readfirstlane_b32 s18, v231
	global_load_lds_dwordx4 v[170:171], off sc1
	s_mov_b32 m0, s18
	v_readfirstlane_b32 s18, v232
	global_load_lds_dwordx4 v[164:165], off sc1
	s_mov_b32 m0, s18
	s_nop 0
	global_load_lds_dwordx4 v[166:167], off sc1
	s_waitcnt lgkmcnt(0)
	v_mfma_f32_32x32x16_bf16 v[48:63], v[64:67], v[72:75], v[48:63]
	s_waitcnt vmcnt(8)
	s_waitcnt lgkmcnt(0)
	s_barrier
	v_mfma_f32_32x32x16_bf16 v[32:47], v[64:67], v[76:79], v[32:47]
	v_mfma_f32_32x32x16_bf16 v[16:31], v[68:71], v[72:75], v[16:31]
	v_mfma_f32_32x32x16_bf16 v[0:15], v[68:71], v[76:79], v[0:15]
	v_mfma_f32_32x32x16_bf16 v[48:63], v[80:83], v[88:91], v[48:63]
	v_mfma_f32_32x32x16_bf16 v[32:47], v[80:83], v[92:95], v[32:47]
	v_mfma_f32_32x32x16_bf16 v[16:31], v[84:87], v[88:91], v[16:31]
	v_mfma_f32_32x32x16_bf16 v[0:15], v[84:87], v[92:95], v[0:15]
	ds_read_b128 v[88:91], v210 offset:16384
	ds_read_b128 v[80:83], v210 offset:18432
	ds_read_b128 v[92:95], v211 offset:24576
	ds_read_b128 v[84:87], v211 offset:26624
	ds_read_b128 v[72:75], v227 offset:16384
	ds_read_b128 v[64:67], v227 offset:18432
	ds_read_b128 v[76:79], v228 offset:24576
	ds_read_b128 v[68:71], v228 offset:26624
	s_cmpk_gt_u32 s30, 0x53
	s_cselect_b64 s[18:19], -1, 0
	s_cmpk_lt_u32 s30, 0x54
	s_cbranch_scc0 .LBB0_34
	s_mov_b64 s[20:21], 0x8056000
	v_lshl_add_u64 v[164:165], v[160:161], 0, s[20:21]
	s_mov_b64 s[20:21], 0x8056400
	v_lshl_add_u64 v[166:167], v[160:161], 0, s[20:21]
	s_mov_b64 s[20:21], 0x16cd6000
	v_lshl_add_u64 v[168:169], v[162:163], 0, s[20:21]
	s_mov_b64 s[20:21], 0x16cd6400
	v_lshl_add_u64 v[170:171], v[162:163], 0, s[20:21]
	v_readfirstlane_b32 s20, v101
	s_mov_b32 m0, s20
	v_readfirstlane_b32 s20, v199
	global_load_lds_dwordx4 v[168:169], off sc1
	s_mov_b32 m0, s20
	v_readfirstlane_b32 s20, v200
	global_load_lds_dwordx4 v[170:171], off sc1
	s_mov_b32 m0, s20
	v_readfirstlane_b32 s20, v201
	global_load_lds_dwordx4 v[164:165], off sc1
	s_mov_b32 m0, s20
	s_nop 0
	global_load_lds_dwordx4 v[166:167], off sc1

.LBB0_42:
	s_waitcnt lgkmcnt(0)
	s_barrier
	ds_read_b128 v[88:91], v210 offset:32768
	ds_read_b128 v[80:83], v210 offset:34816
	ds_read_b128 v[92:95], v211 offset:40960
	ds_read_b128 v[84:87], v211 offset:43008
	ds_read_b128 v[72:75], v227 offset:32768
	ds_read_b128 v[64:67], v227 offset:34816
	ds_read_b128 v[76:79], v228 offset:40960
	ds_read_b128 v[68:71], v228 offset:43008
	s_cmpk_gt_u32 s30, 0x52
	s_cbranch_scc1 .LBB0_44
	s_mov_b64 s[20:21], 0x8058000
	v_lshl_add_u64 v[164:165], v[160:161], 0, s[20:21]
	s_mov_b64 s[20:21], 0x8058400
	v_lshl_add_u64 v[166:167], v[160:161], 0, s[20:21]
	s_mov_b64 s[20:21], 0x16cd8000
	v_lshl_add_u64 v[168:169], v[162:163], 0, s[20:21]
	s_mov_b64 s[20:21], 0x16cd8400
	v_lshl_add_u64 v[170:171], v[162:163], 0, s[20:21]
	v_readfirstlane_b32 s20, v202
	s_mov_b32 m0, s20
	v_readfirstlane_b32 s20, v203
	global_load_lds_dwordx4 v[168:169], off sc1
	s_mov_b32 m0, s20
	v_readfirstlane_b32 s20, v204
	global_load_lds_dwordx4 v[170:171], off sc1
	s_mov_b32 m0, s20
	v_readfirstlane_b32 s20, v205
	global_load_lds_dwordx4 v[164:165], off sc1
	s_mov_b32 m0, s20
	s_nop 0
	global_load_lds_dwordx4 v[166:167], off sc1

.LBB0_48:
	s_waitcnt lgkmcnt(0)
	s_barrier
	ds_read_b128 v[88:91], v210 offset:49152
	ds_read_b128 v[80:83], v210 offset:51200
	ds_read_b128 v[92:95], v211 offset:57344
	ds_read_b128 v[84:87], v211 offset:59392
	ds_read_b128 v[72:75], v227 offset:49152
	ds_read_b128 v[64:67], v227 offset:51200
	ds_read_b128 v[76:79], v228 offset:57344
	ds_read_b128 v[68:71], v228 offset:59392
	s_cmpk_gt_u32 s30, 0x51
	s_cbranch_scc1 .LBB0_31
	s_mov_b64 s[20:21], 0x805a000
	v_lshl_add_u64 v[164:165], v[160:161], 0, s[20:21]
	s_mov_b64 s[20:21], 0x805a400
	v_lshl_add_u64 v[160:161], v[160:161], 0, s[20:21]
	s_mov_b64 s[20:21], 0x16cda000
	v_lshl_add_u64 v[166:167], v[162:163], 0, s[20:21]
	s_mov_b64 s[20:21], 0x16cda400
	v_lshl_add_u64 v[162:163], v[162:163], 0, s[20:21]
	v_readfirstlane_b32 s20, v206
	s_mov_b32 m0, s20
	v_readfirstlane_b32 s20, v207
	global_load_lds_dwordx4 v[166:167], off sc1
	s_mov_b32 m0, s20
	v_readfirstlane_b32 s20, v208
	global_load_lds_dwordx4 v[162:163], off sc1
	s_mov_b32 m0, s20
	v_readfirstlane_b32 s20, v209
	global_load_lds_dwordx4 v[164:165], off sc1
	s_mov_b32 m0, s20
	s_nop 0
	global_load_lds_dwordx4 v[160:161], off sc1
	s_branch .LBB0_31
.LBB0_50:
	s_lshl_b32 s18, s41, 7
	s_add_i32 s16, s18, 0xfffff000
	s_lshr_b32 s16, s16, 10
	s_add_i32 s16, s16, 1
	s_cmp_gt_i32 s41, 31
	s_cselect_b32 s16, s16, 0
	s_mul_i32 s17, s12, 3
	s_add_i32 s16, s16, s17
	s_mul_i32 s19, s16, 0x6000
	s_mul_hi_u32 s17, s16, 0x6000
	s_add_u32 s20, s34, s19
	v_or_b32_e32 v64, s40, v103
	s_addc_u32 s21, s35, s17
	v_lshlrev_b32_e32 v64, 2, v64
	v_mov_b32_e32 v65, v117
	v_lshl_add_u64 v[64:65], s[20:21], 0, v[64:65]
	s_mov_b64 s[20:21], 0x5000
	v_lshl_add_u64 v[66:67], v[64:65], 0, s[20:21]
	v_add_co_u32_e32 v64, vcc, 0x5000, v64
	s_waitcnt lgkmcnt(0)
	s_barrier
	s_nop 0
	v_addc_co_u32_e32 v65, vcc, 0, v65, vcc
	global_load_dword v141, v[64:65], off
	global_load_dword v143, v[66:67], off offset:128
	v_mov_b32_e32 v92, 0
	s_and_b64 vcc, exec, s[0:1]
	v_mov_b32_e32 v93, v92
	v_mov_b32_e32 v94, v92
	v_mov_b32_e32 v95, v92
	s_cbranch_vccz .LBB0_52
	s_add_i32 s16, s16, 3
	s_lshl_b32 s30, s40, 2
	s_mul_hi_u32 s17, s16, 0x6000
	s_mulk_i32 s16, 0x6000
	s_add_u32 s16, s34, s16
	s_addc_u32 s17, s35, s17
	s_add_u32 s16, s16, s30
	s_addc_u32 s17, s17, 0
	v_lshl_add_u64 v[68:69], s[16:17], 0, v[116:117]
	s_movk_i32 s16, 0x1000
	v_add_co_u32_e32 v68, vcc, s16, v68
	v_lshl_add_u64 v[64:65], v[106:107], 0, s[30:31]
	s_nop 0
	v_addc_co_u32_e32 v69, vcc, 0, v69, vcc
	global_load_dwordx4 v[68:71], v[68:69], off sc1
	s_waitcnt vmcnt(0)
	v_pk_add_f32 v[70:71], v[70:71], 1.0 op_sel_hi:[1,0]
	global_load_dwordx4 v[64:67], v[64:65], off sc1
	v_pk_add_f32 v[68:69], v[68:69], 1.0 op_sel_hi:[1,0]
	s_waitcnt vmcnt(0)
	v_pk_mul_f32 v[94:95], v[66:67], v[70:71]
	v_pk_mul_f32 v[92:93], v[64:65], v[68:69]
.LBB0_52:
	v_add_u32_e32 v184, s18, v119
	v_add_u32_e32 v182, s18, v121
	s_lshl_b32 s30, s40, 2
	v_ashrrev_i32_e32 v185, 31, v184
	v_ashrrev_i32_e32 v183, 31, v182
	v_add_u32_e32 v176, s18, v122
	v_add_u32_e32 v174, s18, v125
	v_lshl_add_u64 v[156:157], v[104:105], 0, s[30:31]
	v_lshlrev_b64 v[214:215], 12, v[184:185]
	v_lshlrev_b64 v[216:217], 12, v[182:183]
	v_ashrrev_i32_e32 v177, 31, v176
	v_ashrrev_i32_e32 v175, 31, v174
	v_add_u32_e32 v168, s18, v186
	v_add_u32_e32 v166, s18, v187
	v_lshl_add_u64 v[64:65], v[156:157], 0, v[214:215]
	v_lshl_add_u64 v[66:67], v[156:157], 0, v[216:217]
	v_lshlrev_b64 v[180:181], 12, v[176:177]
	v_lshlrev_b64 v[178:179], 12, v[174:175]
	v_ashrrev_i32_e32 v169, 31, v168
	v_ashrrev_i32_e32 v167, 31, v166
	v_add_u32_e32 v160, s18, v188
	v_add_u32_e32 v158, s18, v189
	global_load_dwordx4 v[238:241], v[64:65], off sc1
	global_load_dwordx4 v[88:91], v[66:67], off sc1
	v_lshl_add_u64 v[64:65], v[156:157], 0, v[180:181]
	v_lshl_add_u64 v[66:67], v[156:157], 0, v[178:179]
	v_lshlrev_b64 v[172:173], 12, v[168:169]
	v_lshlrev_b64 v[170:171], 12, v[166:167]
	v_ashrrev_i32_e32 v161, 31, v160
	v_ashrrev_i32_e32 v159, 31, v158
	global_load_dwordx4 v[84:87], v[64:65], off sc1
	global_load_dwordx4 v[80:83], v[66:67], off sc1
	v_lshl_add_u64 v[64:65], v[156:157], 0, v[172:173]
	v_lshl_add_u64 v[66:67], v[156:157], 0, v[170:171]
	v_lshlrev_b64 v[164:165], 12, v[160:161]
	v_lshlrev_b64 v[162:163], 12, v[158:159]
	global_load_dwordx4 v[76:79], v[64:65], off sc1
	global_load_dwordx4 v[72:75], v[66:67], off sc1
	v_lshl_add_u64 v[64:65], v[156:157], 0, v[164:165]
	v_lshl_add_u64 v[66:67], v[156:157], 0, v[162:163]
	global_load_dwordx4 v[68:71], v[64:65], off sc1
	s_nop 0
	global_load_dwordx4 v[64:67], v[66:67], off sc1
	s_waitcnt vmcnt(0)
	v_mul_f32_e32 v48, v48, v141
	v_mul_f32_e32 v32, v32, v143
	ds_write2_b32 v190, v48, v32 offset1:32
	v_mul_f32_e32 v32, v49, v141
	v_mul_f32_e32 v33, v33, v143
	ds_write2_b32 v190, v32, v33 offset0:132 offset1:164
	v_mul_f32_e32 v32, v50, v141
	v_mul_f32_e32 v33, v34, v143
	v_add_u32_e32 v145, 0x400, v190
	ds_write2_b32 v145, v32, v33 offset0:8 offset1:40
	v_mul_f32_e32 v32, v51, v141
	v_mul_f32_e32 v33, v35, v143
	ds_write2_b32 v145, v32, v33 offset0:140 offset1:172
	v_mul_f32_e32 v32, v52, v141
	v_mul_f32_e32 v33, v36, v143
	v_add_u32_e32 v147, 0x1000, v190
	ds_write2_b32 v147, v32, v33 offset0:32 offset1:64
	v_mul_f32_e32 v32, v53, v141
	v_mul_f32_e32 v33, v37, v143
	ds_write2_b32 v147, v32, v33 offset0:164 offset1:196
	v_mul_f32_e32 v32, v54, v141
	v_mul_f32_e32 v33, v38, v143
	v_add_u32_e32 v149, 0x1400, v190
	ds_write2_b32 v149, v32, v33 offset0:40 offset1:72
	v_mul_f32_e32 v32, v55, v141
	v_mul_f32_e32 v33, v39, v143
	ds_write2_b32 v149, v32, v33 offset0:172 offset1:204
	v_mul_f32_e32 v32, v56, v141
	v_mul_f32_e32 v33, v40, v143
	v_add_u32_e32 v151, 0x2000, v190
	ds_write2_b32 v151, v32, v33 offset0:64 offset1:96
	v_mul_f32_e32 v32, v57, v141
	v_mul_f32_e32 v33, v41, v143
	ds_write2_b32 v151, v32, v33 offset0:196 offset1:228
	v_mul_f32_e32 v32, v58, v141
	v_mul_f32_e32 v33, v42, v143
	v_add_u32_e32 v155, 0x2400, v190
	ds_write2_b32 v155, v32, v33 offset0:72 offset1:104
	v_mul_f32_e32 v32, v59, v141
	v_mul_f32_e32 v33, v43, v143
	ds_write2_b32 v155, v32, v33 offset0:204 offset1:236
	v_mul_f32_e32 v32, v60, v141
	v_mul_f32_e32 v33, v44, v143
	v_add_u32_e32 v234, 0x3000, v190
	ds_write2_b32 v234, v32, v33 offset0:96 offset1:128
	v_mul_f32_e32 v32, v61, v141
	v_mul_f32_e32 v33, v45, v143
	v_add_u32_e32 v235, 0x3200, v190
	ds_write2_b32 v235, v32, v33 offset0:100 offset1:132
	v_mul_f32_e32 v32, v62, v141
	v_mul_f32_e32 v33, v46, v143
	v_add_u32_e32 v236, 0x3400, v190
	ds_write2_b32 v236, v32, v33 offset0:104 offset1:136
	v_mul_f32_e32 v32, v63, v141
	v_mul_f32_e32 v33, v47, v143
	v_add_u32_e32 v237, 0x3600, v190
	ds_write2_b32 v237, v32, v33 offset0:108 offset1:140
	s_waitcnt lgkmcnt(0)
	s_barrier
	ds_read_b128 v[32:35], v233
	v_lshl_add_u64 v[36:37], s[46:47], 0, v[214:215]
	v_lshl_add_u64 v[36:37], v[36:37], 0, s[30:31]
	v_lshl_add_u64 v[36:37], v[36:37], 0, v[116:117]
	s_mov_b64 s[16:17], -1
	s_waitcnt lgkmcnt(0)
	v_pk_add_f32 v[34:35], v[240:241], v[34:35]
	v_pk_add_f32 v[32:33], v[238:239], v[32:33]
	global_store_dwordx4 v[36:37], v[32:35], off
	s_and_b64 vcc, exec, s[8:9]
	v_lshl_add_u64 v[36:37], s[46:47], 0, v[216:217]
	s_cbranch_vccz .LBB0_54
	ds_read_b128 v[38:41], v233 offset:4224
	v_lshl_add_u64 v[42:43], v[36:37], 0, s[30:31]
	v_lshl_add_u64 v[42:43], v[42:43], 0, v[116:117]
	s_mov_b64 s[16:17], 0
	s_waitcnt lgkmcnt(0)
	v_pk_add_f32 v[40:41], v[90:91], v[40:41]
	v_pk_add_f32 v[38:39], v[88:89], v[38:39]
	global_store_dwordx4 v[42:43], v[38:41], off

.LBB0_84:
	v_add_u32_e32 v88, s18, v191
	v_add_u32_e32 v86, s18, v192
	v_ashrrev_i32_e32 v89, 31, v88
	v_ashrrev_i32_e32 v87, 31, v86
	v_add_u32_e32 v80, s18, v193
	v_add_u32_e32 v78, s18, v194
	v_lshlrev_b64 v[90:91], 12, v[88:89]
	v_lshlrev_b64 v[162:163], 12, v[86:87]
	v_ashrrev_i32_e32 v81, 31, v80
	v_ashrrev_i32_e32 v79, 31, v78
	v_add_u32_e32 v72, s18, v195
	v_add_u32_e32 v70, s18, v196
	s_waitcnt lgkmcnt(0)
	v_lshl_add_u64 v[32:33], v[156:157], 0, v[90:91]
	v_lshl_add_u64 v[34:35], v[156:157], 0, v[162:163]
	v_lshlrev_b64 v[84:85], 12, v[80:81]
	v_lshlrev_b64 v[82:83], 12, v[78:79]
	v_ashrrev_i32_e32 v73, 31, v72
	v_ashrrev_i32_e32 v71, 31, v70
	v_add_u32_e32 v64, s18, v197
	v_add_u32_e32 v62, s18, v198
	s_waitcnt lgkmcnt(0)
	s_barrier
	global_load_dwordx4 v[158:161], v[32:33], off sc1
	global_load_dwordx4 v[56:59], v[34:35], off sc1
	v_lshl_add_u64 v[32:33], v[156:157], 0, v[84:85]
	v_lshl_add_u64 v[34:35], v[156:157], 0, v[82:83]
	v_lshlrev_b64 v[76:77], 12, v[72:73]
	v_lshlrev_b64 v[74:75], 12, v[70:71]
	v_ashrrev_i32_e32 v65, 31, v64
	v_ashrrev_i32_e32 v63, 31, v62
	global_load_dwordx4 v[52:55], v[32:33], off sc1
	global_load_dwordx4 v[48:51], v[34:35], off sc1
	v_lshl_add_u64 v[32:33], v[156:157], 0, v[76:77]
	v_lshl_add_u64 v[34:35], v[156:157], 0, v[74:75]
	v_lshlrev_b64 v[68:69], 12, v[64:65]
	v_lshlrev_b64 v[66:67], 12, v[62:63]
	global_load_dwordx4 v[44:47], v[32:33], off sc1
	global_load_dwordx4 v[40:43], v[34:35], off sc1
	v_lshl_add_u64 v[32:33], v[156:157], 0, v[68:69]
	v_lshl_add_u64 v[34:35], v[156:157], 0, v[66:67]
	global_load_dwordx4 v[36:39], v[32:33], off sc1
	s_nop 0
	global_load_dwordx4 v[32:35], v[34:35], off sc1
	v_mul_f32_e32 v16, v16, v141
	v_mul_f32_e32 v0, v0, v143
	ds_write2_b32 v190, v16, v0 offset1:32
	v_mul_f32_e32 v0, v17, v141
	v_mul_f32_e32 v1, v1, v143
	ds_write2_b32 v190, v0, v1 offset0:132 offset1:164
	v_mul_f32_e32 v0, v18, v141
	v_mul_f32_e32 v1, v2, v143
	ds_write2_b32 v145, v0, v1 offset0:8 offset1:40
	v_mul_f32_e32 v0, v19, v141
	v_mul_f32_e32 v1, v3, v143
	ds_write2_b32 v145, v0, v1 offset0:140 offset1:172
	v_mul_f32_e32 v0, v20, v141
	v_mul_f32_e32 v1, v4, v143
	ds_write2_b32 v147, v0, v1 offset0:32 offset1:64
	v_mul_f32_e32 v0, v21, v141
	v_mul_f32_e32 v1, v5, v143
	ds_write2_b32 v147, v0, v1 offset0:164 offset1:196
	v_mul_f32_e32 v0, v22, v141
	v_mul_f32_e32 v1, v6, v143
	ds_write2_b32 v149, v0, v1 offset0:40 offset1:72
	v_mul_f32_e32 v0, v23, v141
	v_mul_f32_e32 v1, v7, v143
	ds_write2_b32 v149, v0, v1 offset0:172 offset1:204
	v_mul_f32_e32 v0, v24, v141
	v_mul_f32_e32 v1, v8, v143
	ds_write2_b32 v151, v0, v1 offset0:64 offset1:96
	v_mul_f32_e32 v0, v25, v141
	v_mul_f32_e32 v1, v9, v143
	ds_write2_b32 v151, v0, v1 offset0:196 offset1:228
	v_mul_f32_e32 v0, v26, v141
	v_mul_f32_e32 v1, v10, v143
	ds_write2_b32 v155, v0, v1 offset0:72 offset1:104
	v_mul_f32_e32 v0, v27, v141
	v_mul_f32_e32 v1, v11, v143
	ds_write2_b32 v155, v0, v1 offset0:204 offset1:236
	v_mul_f32_e32 v0, v28, v141
	v_mul_f32_e32 v1, v12, v143
	ds_write2_b32 v234, v0, v1 offset0:96 offset1:128
	v_mul_f32_e32 v0, v29, v141
	v_mul_f32_e32 v1, v13, v143
	ds_write2_b32 v235, v0, v1 offset0:100 offset1:132
	v_mul_f32_e32 v0, v30, v141
	v_mul_f32_e32 v1, v14, v143
	ds_write2_b32 v236, v0, v1 offset0:104 offset1:136
	v_mul_f32_e32 v0, v31, v141
	v_mul_f32_e32 v1, v15, v143
	ds_write2_b32 v237, v0, v1 offset0:108 offset1:140
	s_waitcnt lgkmcnt(0)
	s_barrier
	ds_read_b128 v[0:3], v233
	v_lshl_add_u64 v[4:5], s[46:47], 0, v[90:91]
	v_lshl_add_u64 v[4:5], v[4:5], 0, s[30:31]
	v_lshl_add_u64 v[4:5], v[4:5], 0, v[116:117]
	s_mov_b64 s[16:17], -1
	s_and_b64 vcc, exec, s[8:9]
	s_waitcnt vmcnt(7) lgkmcnt(0)
	v_pk_add_f32 v[2:3], v[160:161], v[2:3]
	v_pk_add_f32 v[0:1], v[158:159], v[0:1]
	global_store_dwordx4 v[4:5], v[0:3], off
	v_lshl_add_u64 v[4:5], s[46:47], 0, v[162:163]
	s_cbranch_vccz .LBB0_86
	ds_read_b128 v[6:9], v233 offset:4224
	v_lshl_add_u64 v[10:11], v[4:5], 0, s[30:31]
	v_lshl_add_u64 v[10:11], v[10:11], 0, v[116:117]
	s_mov_b64 s[16:17], 0
	s_waitcnt vmcnt(7) lgkmcnt(0)
	v_pk_add_f32 v[8:9], v[58:59], v[8:9]
	v_pk_add_f32 v[6:7], v[56:57], v[6:7]
	global_store_dwordx4 v[10:11], v[6:9], off

.LBB0_128:
	s_xor_b64 s[18:19], s[18:19], -1
	s_xor_b64 s[10:11], s[16:17], -1
	v_mov_b32_e32 v72, 0x358637bd
	s_and_saveexec_b64 s[20:21], s[36:37]
	s_cbranch_execz .LBB0_130
	s_ashr_i32 s1, s0, 31
	v_lshl_add_u64 v[0:1], s[0:1], 2, v[84:85]
	global_load_dword v0, v[0:1], off sc1
	s_waitcnt vmcnt(0)
	v_cvt_f32_u32_e32 v0, v0
	v_fmamk_f32 v72, v0, 0x36800000, v212

.Lgw_skipall:
	s_ashr_i32 s1, s0, 31
	s_lshl_b64 s[22:23], s[0:1], 18
	v_readfirstlane_b32 s43, v101
	v_add_u32_e32 v84, 0x400, v101
	s_and_b32 s20, s18, 0x380
	v_lshl_add_u64 v[64:65], v[96:97], 0, s[22:23]
	s_mov_b32 m0, s43
	s_mov_b64 s[22:23], 0x400
	v_readfirstlane_b32 s41, v84
	v_add_u32_e32 v85, 0x2000, v101
	s_lshl_b32 s30, s20, 11
	global_load_lds_dwordx4 v[64:65], off sc1
	s_waitcnt lgkmcnt(0)
	v_lshl_add_u64 v[0:1], v[64:65], 0, s[22:23]
	s_mov_b32 m0, s41
	v_readfirstlane_b32 s42, v85
	v_add_u32_e32 v86, 0x2400, v101
	v_lshl_add_u64 v[66:67], v[98:99], 0, s[30:31]
	global_load_lds_dwordx4 v[0:1], off sc1
	s_mov_b32 m0, s42
	v_readfirstlane_b32 s48, v86
	v_add_u32_e32 v80, 0x4000, v101
	global_load_lds_dwordx4 v[66:67], off sc1
	v_lshl_add_u64 v[0:1], v[66:67], 0, s[22:23]
	s_mov_b32 m0, s48
	v_readfirstlane_b32 s38, v80
	v_add_u32_e32 v81, 0x4400, v101
	global_load_lds_dwordx4 v[0:1], off sc1
	v_lshl_add_u64 v[0:1], v[64:65], 0, s[44:45]
	s_mov_b32 m0, s38
	v_readfirstlane_b32 s37, v81
	v_add_u32_e32 v82, 0x6000, v101
	global_load_lds_dwordx4 v[0:1], off sc1
	v_lshl_add_u64 v[0:1], v[64:65], 0, s[66:67]
	s_mov_b32 m0, s37
	v_readfirstlane_b32 s39, v82
	v_add_u32_e32 v83, 0x6400, v101
	global_load_lds_dwordx4 v[0:1], off sc1
	v_lshl_add_u64 v[0:1], v[66:67], 0, s[44:45]
	s_mov_b32 m0, s39
	v_readfirstlane_b32 s40, v83
	v_add_u32_e32 v76, 0x8000, v101
	global_load_lds_dwordx4 v[0:1], off sc1
	v_lshl_add_u64 v[0:1], v[66:67], 0, s[66:67]
	s_mov_b32 m0, s40
	v_readfirstlane_b32 s34, v76
	v_add_u32_e32 v77, 0x8400, v101
	global_load_lds_dwordx4 v[0:1], off sc1
	v_lshl_add_u64 v[0:1], v[64:65], 0, s[28:29]
	s_mov_b32 m0, s34
	s_mov_b64 s[22:23], 0x4400
	v_readfirstlane_b32 s30, v77
	v_add_u32_e32 v78, 0xa000, v101
	global_load_lds_dwordx4 v[0:1], off sc1
	v_lshl_add_u64 v[0:1], v[64:65], 0, s[22:23]
	s_mov_b32 m0, s30
	v_readfirstlane_b32 s35, v78
	v_add_u32_e32 v79, 0xa400, v101
	global_load_lds_dwordx4 v[0:1], off sc1
	v_lshl_add_u64 v[0:1], v[66:67], 0, s[28:29]
	s_mov_b32 m0, s35
	v_readfirstlane_b32 s36, v79
	global_load_lds_dwordx4 v[0:1], off sc1
	v_lshl_add_u64 v[0:1], v[66:67], 0, s[22:23]
	s_mov_b32 m0, s36
	v_add_u32_e32 v68, v125, v121
	global_load_lds_dwordx4 v[0:1], off sc1
	s_waitcnt vmcnt(8)
	v_add_u32_e32 v69, v122, v121
	v_add_u32_e32 v70, v125, v119
	v_add_u32_e32 v71, v122, v119
	s_waitcnt lgkmcnt(0)
	s_barrier
	ds_read_b128 v[0:3], v68
	ds_read_b128 v[16:19], v68 offset:2048
	ds_read_b128 v[4:7], v69 offset:8192
	ds_read_b128 v[20:23], v69 offset:10240
	ds_read_b128 v[88:91], v70
	ds_read_b128 v[92:95], v70 offset:2048
	ds_read_b128 v[152:155], v71 offset:8192
	ds_read_b128 v[156:159], v71 offset:10240
	s_mov_b64 s[22:23], 0x6000
	v_add_u32_e32 v72, 0xc000, v101
	v_lshl_add_u64 v[8:9], v[66:67], 0, s[22:23]
	v_lshl_add_u64 v[14:15], v[64:65], 0, s[22:23]
	v_readfirstlane_b32 s22, v72
	v_add_u32_e32 v73, 0xc400, v101
	s_mov_b64 s[64:65], 0x6400
	s_mov_b32 m0, s22
	v_readfirstlane_b32 s1, v73
	v_add_u32_e32 v74, 0xe000, v101
	v_lshl_add_u64 v[12:13], v[64:65], 0, s[64:65]
	global_load_lds_dwordx4 v[14:15], off sc1
	s_mov_b32 m0, s1
	v_readfirstlane_b32 s21, v74
	v_add_u32_e32 v75, 0xe400, v101
	global_load_lds_dwordx4 v[12:13], off sc1
	s_mov_b32 m0, s21
	v_readfirstlane_b32 s23, v75
	v_lshl_add_u64 v[10:11], v[66:67], 0, s[64:65]
	global_load_lds_dwordx4 v[8:9], off sc1
	s_mov_b32 m0, s23
	s_nop 0
	global_load_lds_dwordx4 v[10:11], off sc1
	s_waitcnt lgkmcnt(0)
	v_mfma_f32_32x32x16_bf16 v[32:47], v[0:3], v[4:7], 0
	s_waitcnt vmcnt(8)
	s_waitcnt lgkmcnt(0)
	s_barrier
	v_mfma_f32_32x32x16_bf16 v[48:63], v[0:3], v[20:23], 0
	v_mfma_f32_32x32x16_bf16 v[0:15], v[16:19], v[4:7], 0
	v_mfma_f32_32x32x16_bf16 v[16:31], v[16:19], v[20:23], 0
	v_mfma_f32_32x32x16_bf16 v[32:47], v[88:91], v[152:155], v[32:47]
	v_mfma_f32_32x32x16_bf16 v[48:63], v[88:91], v[156:159], v[48:63]
	v_mfma_f32_32x32x16_bf16 v[0:15], v[92:95], v[152:155], v[0:15]
	v_mfma_f32_32x32x16_bf16 v[16:31], v[92:95], v[156:159], v[16:31]
	ds_read_b128 v[88:91], v68 offset:16384
	ds_read_b128 v[92:95], v68 offset:18432
	ds_read_b128 v[152:155], v69 offset:24576
	ds_read_b128 v[156:159], v69 offset:26624
	ds_read_b128 v[160:163], v70 offset:16384
	ds_read_b128 v[164:167], v70 offset:18432
	ds_read_b128 v[168:171], v71 offset:24576
	ds_read_b128 v[172:175], v71 offset:26624
	s_mov_b64 s[64:65], 0x8000
	s_mov_b32 m0, s43
	s_mov_b64 s[68:69], 0x8400
	v_lshl_add_u64 v[182:183], v[64:65], 0, s[64:65]
	v_lshl_add_u64 v[180:181], v[64:65], 0, s[68:69]
	global_load_lds_dwordx4 v[182:183], off sc1
	s_mov_b32 m0, s41
	v_lshl_add_u64 v[176:177], v[66:67], 0, s[64:65]
	global_load_lds_dwordx4 v[180:181], off sc1
	s_mov_b32 m0, s42
	v_lshl_add_u64 v[178:179], v[66:67], 0, s[68:69]
	global_load_lds_dwordx4 v[176:177], off sc1
	s_mov_b32 m0, s48
	s_nop 0
	global_load_lds_dwordx4 v[178:179], off sc1
	s_waitcnt lgkmcnt(0)
	v_mfma_f32_32x32x16_bf16 v[32:47], v[88:91], v[152:155], v[32:47]
	s_waitcnt vmcnt(8)
	s_waitcnt lgkmcnt(0)
	s_barrier
	v_mfma_f32_32x32x16_bf16 v[48:63], v[88:91], v[156:159], v[48:63]
	v_mfma_f32_32x32x16_bf16 v[0:15], v[92:95], v[152:155], v[0:15]
	v_mfma_f32_32x32x16_bf16 v[16:31], v[92:95], v[156:159], v[16:31]
	v_mfma_f32_32x32x16_bf16 v[32:47], v[160:163], v[168:171], v[32:47]
	v_mfma_f32_32x32x16_bf16 v[48:63], v[160:163], v[172:175], v[48:63]
	v_mfma_f32_32x32x16_bf16 v[0:15], v[164:167], v[168:171], v[0:15]
	v_mfma_f32_32x32x16_bf16 v[16:31], v[164:167], v[172:175], v[16:31]
	ds_read_b128 v[88:91], v68 offset:32768
	ds_read_b128 v[92:95], v68 offset:34816
	ds_read_b128 v[152:155], v69 offset:40960
	ds_read_b128 v[156:159], v69 offset:43008
	ds_read_b128 v[160:163], v70 offset:32768
	ds_read_b128 v[164:167], v70 offset:34816
	ds_read_b128 v[168:171], v71 offset:40960
	ds_read_b128 v[172:175], v71 offset:43008
	s_mov_b64 s[64:65], 0xa000
	s_mov_b32 m0, s38
	s_mov_b64 s[68:69], 0xa400
	v_lshl_add_u64 v[182:183], v[64:65], 0, s[64:65]
	v_lshl_add_u64 v[180:181], v[64:65], 0, s[68:69]
	global_load_lds_dwordx4 v[182:183], off sc1
	s_mov_b32 m0, s37
	v_lshl_add_u64 v[176:177], v[66:67], 0, s[64:65]
	global_load_lds_dwordx4 v[180:181], off sc1
	s_mov_b32 m0, s39
	v_lshl_add_u64 v[178:179], v[66:67], 0, s[68:69]
	global_load_lds_dwordx4 v[176:177], off sc1
	s_mov_b32 m0, s40
	s_nop 0
	global_load_lds_dwordx4 v[178:179], off sc1
	s_waitcnt lgkmcnt(0)
	v_mfma_f32_32x32x16_bf16 v[32:47], v[88:91], v[152:155], v[32:47]
	s_waitcnt vmcnt(8)
	s_waitcnt lgkmcnt(0)
	s_barrier
	v_mfma_f32_32x32x16_bf16 v[48:63], v[88:91], v[156:159], v[48:63]
	v_mfma_f32_32x32x16_bf16 v[0:15], v[92:95], v[152:155], v[0:15]
	v_mfma_f32_32x32x16_bf16 v[16:31], v[92:95], v[156:159], v[16:31]
	v_mfma_f32_32x32x16_bf16 v[32:47], v[160:163], v[168:171], v[32:47]
	v_mfma_f32_32x32x16_bf16 v[48:63], v[160:163], v[172:175], v[48:63]
	v_mfma_f32_32x32x16_bf16 v[0:15], v[164:167], v[168:171], v[0:15]
	v_mfma_f32_32x32x16_bf16 v[16:31], v[164:167], v[172:175], v[16:31]
	ds_read_b128 v[88:91], v68 offset:49152
	ds_read_b128 v[92:95], v68 offset:51200
	ds_read_b128 v[152:155], v69 offset:57344
	ds_read_b128 v[156:159], v69 offset:59392
	ds_read_b128 v[160:163], v70 offset:49152
	ds_read_b128 v[164:167], v70 offset:51200
	ds_read_b128 v[168:171], v71 offset:57344
	ds_read_b128 v[172:175], v71 offset:59392
	s_mov_b64 s[64:65], 0xc000
	s_mov_b32 m0, s34
	s_mov_b64 s[68:69], 0xc400
	v_lshl_add_u64 v[182:183], v[64:65], 0, s[64:65]
	v_lshl_add_u64 v[180:181], v[64:65], 0, s[68:69]
	global_load_lds_dwordx4 v[182:183], off sc1
	s_mov_b32 m0, s30
	v_lshl_add_u64 v[176:177], v[66:67], 0, s[64:65]
	global_load_lds_dwordx4 v[180:181], off sc1
	s_mov_b32 m0, s35
	v_lshl_add_u64 v[178:179], v[66:67], 0, s[68:69]
	global_load_lds_dwordx4 v[176:177], off sc1
	s_mov_b32 m0, s36
	s_nop 0
	global_load_lds_dwordx4 v[178:179], off sc1
	s_waitcnt lgkmcnt(0)
	v_mfma_f32_32x32x16_bf16 v[32:47], v[88:91], v[152:155], v[32:47]
	s_waitcnt vmcnt(8)
	s_waitcnt lgkmcnt(0)
	s_barrier
	v_mfma_f32_32x32x16_bf16 v[48:63], v[88:91], v[156:159], v[48:63]
	v_mfma_f32_32x32x16_bf16 v[0:15], v[92:95], v[152:155], v[0:15]
	v_mfma_f32_32x32x16_bf16 v[16:31], v[92:95], v[156:159], v[16:31]
	v_mfma_f32_32x32x16_bf16 v[32:47], v[160:163], v[168:171], v[32:47]
	v_mfma_f32_32x32x16_bf16 v[48:63], v[160:163], v[172:175], v[48:63]
	v_mfma_f32_32x32x16_bf16 v[0:15], v[164:167], v[168:171], v[0:15]
	v_mfma_f32_32x32x16_bf16 v[16:31], v[164:167], v[172:175], v[16:31]
	ds_read_b128 v[88:91], v68
	ds_read_b128 v[92:95], v68 offset:2048
	ds_read_b128 v[152:155], v69 offset:8192
	ds_read_b128 v[156:159], v69 offset:10240
	ds_read_b128 v[160:163], v70
	ds_read_b128 v[164:167], v70 offset:2048
	ds_read_b128 v[168:171], v71 offset:8192
	ds_read_b128 v[172:175], v71 offset:10240
	s_mov_b64 s[68:69], 0xe000
	s_mov_b32 m0, s22
	s_mov_b64 s[64:65], 0xe400
	v_lshl_add_u64 v[182:183], v[64:65], 0, s[68:69]
	v_lshl_add_u64 v[180:181], v[64:65], 0, s[64:65]
	global_load_lds_dwordx4 v[182:183], off sc1
	s_mov_b32 m0, s1
	v_lshl_add_u64 v[176:177], v[66:67], 0, s[68:69]
	global_load_lds_dwordx4 v[180:181], off sc1
	s_mov_b32 m0, s21
	v_lshl_add_u64 v[178:179], v[66:67], 0, s[64:65]
	global_load_lds_dwordx4 v[176:177], off sc1
	s_mov_b32 m0, s23
	s_nop 0
	global_load_lds_dwordx4 v[178:179], off sc1
	s_waitcnt lgkmcnt(0)
	v_mfma_f32_32x32x16_bf16 v[32:47], v[88:91], v[152:155], v[32:47]
	s_waitcnt vmcnt(8)
	s_waitcnt lgkmcnt(0)
	s_barrier
	v_mfma_f32_32x32x16_bf16 v[48:63], v[88:91], v[156:159], v[48:63]
	v_mfma_f32_32x32x16_bf16 v[0:15], v[92:95], v[152:155], v[0:15]
	v_mfma_f32_32x32x16_bf16 v[16:31], v[92:95], v[156:159], v[16:31]
	v_mfma_f32_32x32x16_bf16 v[32:47], v[160:163], v[168:171], v[32:47]
	v_mfma_f32_32x32x16_bf16 v[48:63], v[160:163], v[172:175], v[48:63]
	v_mfma_f32_32x32x16_bf16 v[0:15], v[164:167], v[168:171], v[0:15]
	v_mfma_f32_32x32x16_bf16 v[16:31], v[164:167], v[172:175], v[16:31]
	ds_read_b128 v[88:91], v68 offset:16384
	ds_read_b128 v[92:95], v68 offset:18432
	ds_read_b128 v[152:155], v69 offset:24576
	ds_read_b128 v[156:159], v69 offset:26624
	ds_read_b128 v[160:163], v70 offset:16384
	ds_read_b128 v[164:167], v70 offset:18432
	ds_read_b128 v[168:171], v71 offset:24576
	ds_read_b128 v[172:175], v71 offset:26624
	s_mov_b64 s[68:69], 0x10000
	s_mov_b32 m0, s43
	s_mov_b64 s[64:65], 0x10400
	v_lshl_add_u64 v[182:183], v[64:65], 0, s[68:69]
	v_lshl_add_u64 v[180:181], v[64:65], 0, s[64:65]
	global_load_lds_dwordx4 v[182:183], off sc1
	s_mov_b32 m0, s41
	v_lshl_add_u64 v[176:177], v[66:67], 0, s[68:69]
	global_load_lds_dwordx4 v[180:181], off sc1
	s_mov_b32 m0, s42
	v_lshl_add_u64 v[178:179], v[66:67], 0, s[64:65]
	global_load_lds_dwordx4 v[176:177], off sc1
	s_mov_b32 m0, s48
	s_nop 0
	global_load_lds_dwordx4 v[178:179], off sc1
	s_waitcnt lgkmcnt(0)
	v_mfma_f32_32x32x16_bf16 v[32:47], v[88:91], v[152:155], v[32:47]
	s_waitcnt vmcnt(8)
	s_waitcnt lgkmcnt(0)
	s_barrier
	v_mfma_f32_32x32x16_bf16 v[48:63], v[88:91], v[156:159], v[48:63]
	v_mfma_f32_32x32x16_bf16 v[0:15], v[92:95], v[152:155], v[0:15]
	v_mfma_f32_32x32x16_bf16 v[16:31], v[92:95], v[156:159], v[16:31]
	v_mfma_f32_32x32x16_bf16 v[32:47], v[160:163], v[168:171], v[32:47]
	v_mfma_f32_32x32x16_bf16 v[48:63], v[160:163], v[172:175], v[48:63]
	v_mfma_f32_32x32x16_bf16 v[0:15], v[164:167], v[168:171], v[0:15]
	v_mfma_f32_32x32x16_bf16 v[16:31], v[164:167], v[172:175], v[16:31]
	ds_read_b128 v[88:91], v68 offset:32768
	ds_read_b128 v[92:95], v68 offset:34816
	ds_read_b128 v[152:155], v69 offset:40960
	ds_read_b128 v[156:159], v69 offset:43008
	ds_read_b128 v[160:163], v70 offset:32768
	ds_read_b128 v[164:167], v70 offset:34816
	ds_read_b128 v[168:171], v71 offset:40960
	ds_read_b128 v[172:175], v71 offset:43008
	s_mov_b64 s[68:69], 0x12000
	s_mov_b32 m0, s38
	s_mov_b64 s[64:65], 0x12400
	v_lshl_add_u64 v[182:183], v[64:65], 0, s[68:69]
	v_lshl_add_u64 v[180:181], v[64:65], 0, s[64:65]
	global_load_lds_dwordx4 v[182:183], off sc1
	s_mov_b32 m0, s37
	v_lshl_add_u64 v[176:177], v[66:67], 0, s[68:69]
	global_load_lds_dwordx4 v[180:181], off sc1
	s_mov_b32 m0, s39
	v_lshl_add_u64 v[178:179], v[66:67], 0, s[64:65]
	global_load_lds_dwordx4 v[176:177], off sc1
	s_mov_b32 m0, s40
	s_nop 0
	global_load_lds_dwordx4 v[178:179], off sc1
	s_waitcnt lgkmcnt(0)
	v_mfma_f32_32x32x16_bf16 v[32:47], v[88:91], v[152:155], v[32:47]
	s_waitcnt vmcnt(8)
	s_waitcnt lgkmcnt(0)
	s_barrier
	v_mfma_f32_32x32x16_bf16 v[48:63], v[88:91], v[156:159], v[48:63]
	v_mfma_f32_32x32x16_bf16 v[0:15], v[92:95], v[152:155], v[0:15]
	v_mfma_f32_32x32x16_bf16 v[16:31], v[92:95], v[156:159], v[16:31]
	v_mfma_f32_32x32x16_bf16 v[32:47], v[160:163], v[168:171], v[32:47]
	v_mfma_f32_32x32x16_bf16 v[48:63], v[160:163], v[172:175], v[48:63]
	v_mfma_f32_32x32x16_bf16 v[0:15], v[164:167], v[168:171], v[0:15]
	v_mfma_f32_32x32x16_bf16 v[16:31], v[164:167], v[172:175], v[16:31]
	ds_read_b128 v[88:91], v68 offset:49152
	ds_read_b128 v[92:95], v68 offset:51200
	ds_read_b128 v[152:155], v69 offset:57344
	ds_read_b128 v[156:159], v69 offset:59392
	ds_read_b128 v[160:163], v70 offset:49152
	ds_read_b128 v[164:167], v70 offset:51200
	ds_read_b128 v[168:171], v71 offset:57344
	ds_read_b128 v[172:175], v71 offset:59392
	s_mov_b64 s[68:69], 0x14000
	s_mov_b32 m0, s34
	s_mov_b64 s[64:65], 0x14400
	v_lshl_add_u64 v[182:183], v[64:65], 0, s[68:69]
	v_lshl_add_u64 v[180:181], v[64:65], 0, s[64:65]
	global_load_lds_dwordx4 v[182:183], off sc1
	s_mov_b32 m0, s30
	v_lshl_add_u64 v[176:177], v[66:67], 0, s[68:69]
	global_load_lds_dwordx4 v[180:181], off sc1
	s_mov_b32 m0, s35
	v_lshl_add_u64 v[178:179], v[66:67], 0, s[64:65]
	global_load_lds_dwordx4 v[176:177], off sc1
	s_mov_b32 m0, s36
	s_nop 0
	global_load_lds_dwordx4 v[178:179], off sc1
	s_waitcnt lgkmcnt(0)
	v_mfma_f32_32x32x16_bf16 v[32:47], v[88:91], v[152:155], v[32:47]
	s_waitcnt vmcnt(8)
	s_waitcnt lgkmcnt(0)
	s_barrier
	v_mfma_f32_32x32x16_bf16 v[48:63], v[88:91], v[156:159], v[48:63]
	v_mfma_f32_32x32x16_bf16 v[0:15], v[92:95], v[152:155], v[0:15]
	v_mfma_f32_32x32x16_bf16 v[16:31], v[92:95], v[156:159], v[16:31]
	v_mfma_f32_32x32x16_bf16 v[32:47], v[160:163], v[168:171], v[32:47]
	v_mfma_f32_32x32x16_bf16 v[48:63], v[160:163], v[172:175], v[48:63]
	v_mfma_f32_32x32x16_bf16 v[0:15], v[164:167], v[168:171], v[0:15]
	v_mfma_f32_32x32x16_bf16 v[16:31], v[164:167], v[172:175], v[16:31]
	ds_read_b128 v[88:91], v68
	ds_read_b128 v[92:95], v68 offset:2048
	ds_read_b128 v[152:155], v69 offset:8192
	ds_read_b128 v[156:159], v69 offset:10240
	ds_read_b128 v[160:163], v70
	ds_read_b128 v[164:167], v70 offset:2048
	ds_read_b128 v[168:171], v71 offset:8192
	ds_read_b128 v[172:175], v71 offset:10240
	s_mov_b64 s[68:69], 0x16000
	s_mov_b32 m0, s22
	s_mov_b64 s[64:65], 0x16400
	v_lshl_add_u64 v[182:183], v[64:65], 0, s[68:69]
	v_lshl_add_u64 v[180:181], v[64:65], 0, s[64:65]
	global_load_lds_dwordx4 v[182:183], off sc1
	s_mov_b32 m0, s1
	v_lshl_add_u64 v[176:177], v[66:67], 0, s[68:69]
	global_load_lds_dwordx4 v[180:181], off sc1
	s_mov_b32 m0, s21
	v_lshl_add_u64 v[178:179], v[66:67], 0, s[64:65]
	global_load_lds_dwordx4 v[176:177], off sc1
	s_mov_b32 m0, s23
	s_nop 0
	global_load_lds_dwordx4 v[178:179], off sc1
	s_waitcnt lgkmcnt(0)
	v_mfma_f32_32x32x16_bf16 v[32:47], v[88:91], v[152:155], v[32:47]
	s_waitcnt vmcnt(8)
	s_waitcnt lgkmcnt(0)
	s_barrier
	v_mfma_f32_32x32x16_bf16 v[48:63], v[88:91], v[156:159], v[48:63]
	v_mfma_f32_32x32x16_bf16 v[0:15], v[92:95], v[152:155], v[0:15]
	v_mfma_f32_32x32x16_bf16 v[16:31], v[92:95], v[156:159], v[16:31]
	v_mfma_f32_32x32x16_bf16 v[32:47], v[160:163], v[168:171], v[32:47]
	v_mfma_f32_32x32x16_bf16 v[48:63], v[160:163], v[172:175], v[48:63]
	v_mfma_f32_32x32x16_bf16 v[0:15], v[164:167], v[168:171], v[0:15]
	v_mfma_f32_32x32x16_bf16 v[16:31], v[164:167], v[172:175], v[16:31]
	ds_read_b128 v[88:91], v68 offset:16384
	ds_read_b128 v[92:95], v68 offset:18432
	ds_read_b128 v[152:155], v69 offset:24576
	ds_read_b128 v[156:159], v69 offset:26624
	ds_read_b128 v[160:163], v70 offset:16384
	ds_read_b128 v[164:167], v70 offset:18432
	ds_read_b128 v[168:171], v71 offset:24576
	ds_read_b128 v[172:175], v71 offset:26624
	s_mov_b64 s[68:69], 0x18000
	s_mov_b32 m0, s43
	s_mov_b64 s[64:65], 0x18400
	v_lshl_add_u64 v[182:183], v[64:65], 0, s[68:69]
	v_lshl_add_u64 v[180:181], v[64:65], 0, s[64:65]
	global_load_lds_dwordx4 v[182:183], off sc1
	s_mov_b32 m0, s41
	v_lshl_add_u64 v[176:177], v[66:67], 0, s[68:69]
	global_load_lds_dwordx4 v[180:181], off sc1
	s_mov_b32 m0, s42
	v_lshl_add_u64 v[178:179], v[66:67], 0, s[64:65]
	global_load_lds_dwordx4 v[176:177], off sc1
	s_mov_b32 m0, s48
	s_nop 0
	global_load_lds_dwordx4 v[178:179], off sc1
	s_waitcnt lgkmcnt(0)
	v_mfma_f32_32x32x16_bf16 v[32:47], v[88:91], v[152:155], v[32:47]
	s_waitcnt vmcnt(8)
	s_waitcnt lgkmcnt(0)
	s_barrier
	v_mfma_f32_32x32x16_bf16 v[48:63], v[88:91], v[156:159], v[48:63]
	v_mfma_f32_32x32x16_bf16 v[0:15], v[92:95], v[152:155], v[0:15]
	v_mfma_f32_32x32x16_bf16 v[16:31], v[92:95], v[156:159], v[16:31]
	v_mfma_f32_32x32x16_bf16 v[32:47], v[160:163], v[168:171], v[32:47]
	v_mfma_f32_32x32x16_bf16 v[48:63], v[160:163], v[172:175], v[48:63]
	v_mfma_f32_32x32x16_bf16 v[0:15], v[164:167], v[168:171], v[0:15]
	v_mfma_f32_32x32x16_bf16 v[16:31], v[164:167], v[172:175], v[16:31]
	ds_read_b128 v[88:91], v68 offset:32768
	ds_read_b128 v[92:95], v68 offset:34816
	ds_read_b128 v[152:155], v69 offset:40960
	ds_read_b128 v[156:159], v69 offset:43008
	ds_read_b128 v[160:163], v70 offset:32768
	ds_read_b128 v[164:167], v70 offset:34816
	ds_read_b128 v[168:171], v71 offset:40960
	ds_read_b128 v[172:175], v71 offset:43008
	s_mov_b64 s[48:49], 0x1a000
	s_mov_b32 m0, s38
	s_mov_b64 s[42:43], 0x1a400
	v_lshl_add_u64 v[182:183], v[64:65], 0, s[48:49]
	v_lshl_add_u64 v[180:181], v[64:65], 0, s[42:43]
	global_load_lds_dwordx4 v[182:183], off sc1
	s_mov_b32 m0, s37
	v_lshl_add_u64 v[176:177], v[66:67], 0, s[48:49]
	global_load_lds_dwordx4 v[180:181], off sc1
	s_mov_b32 m0, s39
	v_lshl_add_u64 v[178:179], v[66:67], 0, s[42:43]
	global_load_lds_dwordx4 v[176:177], off sc1
	s_mov_b32 m0, s40
	s_nop 0
	global_load_lds_dwordx4 v[178:179], off sc1
	s_waitcnt lgkmcnt(0)
	v_mfma_f32_32x32x16_bf16 v[32:47], v[88:91], v[152:155], v[32:47]
	s_waitcnt vmcnt(8)
	s_waitcnt lgkmcnt(0)
	s_barrier
	v_mfma_f32_32x32x16_bf16 v[48:63], v[88:91], v[156:159], v[48:63]
	v_mfma_f32_32x32x16_bf16 v[0:15], v[92:95], v[152:155], v[0:15]
	v_mfma_f32_32x32x16_bf16 v[16:31], v[92:95], v[156:159], v[16:31]
	v_mfma_f32_32x32x16_bf16 v[32:47], v[160:163], v[168:171], v[32:47]
	v_mfma_f32_32x32x16_bf16 v[48:63], v[160:163], v[172:175], v[48:63]
	v_mfma_f32_32x32x16_bf16 v[0:15], v[164:167], v[168:171], v[0:15]
	v_mfma_f32_32x32x16_bf16 v[16:31], v[164:167], v[172:175], v[16:31]
	ds_read_b128 v[88:91], v68 offset:49152
	ds_read_b128 v[92:95], v68 offset:51200
	ds_read_b128 v[152:155], v69 offset:57344
	ds_read_b128 v[156:159], v69 offset:59392
	ds_read_b128 v[160:163], v70 offset:49152
	ds_read_b128 v[164:167], v70 offset:51200
	ds_read_b128 v[168:171], v71 offset:57344
	ds_read_b128 v[172:175], v71 offset:59392
	s_mov_b64 s[40:41], 0x1c000
	s_mov_b32 m0, s34
	s_mov_b64 s[38:39], 0x1c400
	v_lshl_add_u64 v[182:183], v[64:65], 0, s[40:41]
	v_lshl_add_u64 v[180:181], v[64:65], 0, s[38:39]
	global_load_lds_dwordx4 v[182:183], off sc1
	s_mov_b32 m0, s30
	v_lshl_add_u64 v[176:177], v[66:67], 0, s[40:41]
	global_load_lds_dwordx4 v[180:181], off sc1
	s_mov_b32 m0, s35
	v_lshl_add_u64 v[178:179], v[66:67], 0, s[38:39]
	global_load_lds_dwordx4 v[176:177], off sc1
	s_mov_b32 m0, s36
	s_nop 0
	global_load_lds_dwordx4 v[178:179], off sc1
	s_waitcnt lgkmcnt(0)
	v_mfma_f32_32x32x16_bf16 v[32:47], v[88:91], v[152:155], v[32:47]
	s_waitcnt vmcnt(8)
	s_waitcnt lgkmcnt(0)
	s_barrier
	v_mfma_f32_32x32x16_bf16 v[48:63], v[88:91], v[156:159], v[48:63]
	v_mfma_f32_32x32x16_bf16 v[0:15], v[92:95], v[152:155], v[0:15]
	v_mfma_f32_32x32x16_bf16 v[16:31], v[92:95], v[156:159], v[16:31]
	v_mfma_f32_32x32x16_bf16 v[32:47], v[160:163], v[168:171], v[32:47]
	v_mfma_f32_32x32x16_bf16 v[48:63], v[160:163], v[172:175], v[48:63]
	v_mfma_f32_32x32x16_bf16 v[0:15], v[164:167], v[168:171], v[0:15]
	v_mfma_f32_32x32x16_bf16 v[16:31], v[164:167], v[172:175], v[16:31]
	ds_read_b128 v[88:91], v68
	ds_read_b128 v[92:95], v68 offset:2048
	ds_read_b128 v[152:155], v69 offset:8192
	ds_read_b128 v[156:159], v69 offset:10240
	ds_read_b128 v[160:163], v70
	ds_read_b128 v[164:167], v70 offset:2048
	ds_read_b128 v[168:171], v71 offset:8192
	ds_read_b128 v[172:175], v71 offset:10240
	s_mov_b64 s[36:37], 0x1e000
	s_mov_b32 m0, s22
	s_mov_b64 s[34:35], 0x1e400
	v_lshl_add_u64 v[182:183], v[64:65], 0, s[36:37]
	v_lshl_add_u64 v[180:181], v[64:65], 0, s[34:35]
	global_load_lds_dwordx4 v[182:183], off sc1
	s_mov_b32 m0, s1
	v_lshl_add_u64 v[176:177], v[66:67], 0, s[36:37]
	global_load_lds_dwordx4 v[180:181], off sc1
	s_mov_b32 m0, s21
	v_lshl_add_u64 v[178:179], v[66:67], 0, s[34:35]
	global_load_lds_dwordx4 v[176:177], off sc1
	s_mov_b32 m0, s23
	s_nop 0
	global_load_lds_dwordx4 v[178:179], off sc1
	s_waitcnt lgkmcnt(0)
	v_mfma_f32_32x32x16_bf16 v[32:47], v[88:91], v[152:155], v[32:47]
	s_waitcnt vmcnt(8)
	s_waitcnt lgkmcnt(0)
	s_barrier
	v_mfma_f32_32x32x16_bf16 v[48:63], v[88:91], v[156:159], v[48:63]
	v_mfma_f32_32x32x16_bf16 v[0:15], v[92:95], v[152:155], v[0:15]
	v_mfma_f32_32x32x16_bf16 v[16:31], v[92:95], v[156:159], v[16:31]
	v_mfma_f32_32x32x16_bf16 v[32:47], v[160:163], v[168:171], v[32:47]
	v_mfma_f32_32x32x16_bf16 v[48:63], v[160:163], v[172:175], v[48:63]
	v_mfma_f32_32x32x16_bf16 v[0:15], v[164:167], v[168:171], v[0:15]
	v_mfma_f32_32x32x16_bf16 v[16:31], v[164:167], v[172:175], v[16:31]
	ds_read_b128 v[88:91], v68 offset:16384
	ds_read_b128 v[92:95], v68 offset:18432
	ds_read_b128 v[152:155], v69 offset:24576
	ds_read_b128 v[156:159], v69 offset:26624
	ds_read_b128 v[160:163], v70 offset:16384
	ds_read_b128 v[164:167], v70 offset:18432
	ds_read_b128 v[168:171], v71 offset:24576
	ds_read_b128 v[172:175], v71 offset:26624
	s_mov_b64 s[34:35], 0x20000
	v_lshl_add_u64 v[176:177], v[66:67], 0, s[34:35]
	v_lshl_add_u64 v[182:183], v[64:65], 0, s[34:35]
	v_readfirstlane_b32 s34, v101
	s_mov_b64 s[22:23], 0x20400
	s_mov_b32 m0, s34
	v_readfirstlane_b32 s1, v84
	v_lshl_add_u64 v[180:181], v[64:65], 0, s[22:23]
	global_load_lds_dwordx4 v[182:183], off sc1
	s_mov_b32 m0, s1
	v_readfirstlane_b32 s21, v85
	v_lshl_add_u64 v[178:179], v[66:67], 0, s[22:23]
	global_load_lds_dwordx4 v[180:181], off sc1
	s_mov_b32 m0, s21
	v_readfirstlane_b32 s22, v86
	global_load_lds_dwordx4 v[176:177], off sc1
	s_mov_b32 m0, s22
	s_nop 0
	global_load_lds_dwordx4 v[178:179], off sc1
	s_waitcnt lgkmcnt(0)
	v_mfma_f32_32x32x16_bf16 v[32:47], v[88:91], v[152:155], v[32:47]
	s_waitcnt vmcnt(8)
	s_waitcnt lgkmcnt(0)
	s_barrier
	v_mfma_f32_32x32x16_bf16 v[48:63], v[88:91], v[156:159], v[48:63]
	v_mfma_f32_32x32x16_bf16 v[0:15], v[92:95], v[152:155], v[0:15]
	v_mfma_f32_32x32x16_bf16 v[16:31], v[92:95], v[156:159], v[16:31]
	v_mfma_f32_32x32x16_bf16 v[32:47], v[160:163], v[168:171], v[32:47]
	v_mfma_f32_32x32x16_bf16 v[48:63], v[160:163], v[172:175], v[48:63]
	v_mfma_f32_32x32x16_bf16 v[0:15], v[164:167], v[168:171], v[0:15]
	v_mfma_f32_32x32x16_bf16 v[16:31], v[164:167], v[172:175], v[16:31]
	ds_read_b128 v[84:87], v68 offset:32768
	ds_read_b128 v[88:91], v68 offset:34816
	ds_read_b128 v[92:95], v69 offset:40960
	ds_read_b128 v[152:155], v69 offset:43008
	ds_read_b128 v[156:159], v70 offset:32768
	ds_read_b128 v[160:163], v70 offset:34816
	ds_read_b128 v[164:167], v71 offset:40960
	ds_read_b128 v[168:171], v71 offset:43008
	s_mov_b64 s[38:39], 0x22000
	v_lshl_add_u64 v[172:173], v[66:67], 0, s[38:39]
	v_lshl_add_u64 v[178:179], v[64:65], 0, s[38:39]
	v_readfirstlane_b32 s38, v80
	s_mov_b64 s[36:37], 0x22400
	s_mov_b32 m0, s38
	v_readfirstlane_b32 s23, v81
	v_lshl_add_u64 v[176:177], v[64:65], 0, s[36:37]
	global_load_lds_dwordx4 v[178:179], off sc1
	s_mov_b32 m0, s23
	v_readfirstlane_b32 s30, v82
	global_load_lds_dwordx4 v[176:177], off sc1
	s_mov_b32 m0, s30
	v_readfirstlane_b32 s35, v83
	v_lshl_add_u64 v[174:175], v[66:67], 0, s[36:37]
	global_load_lds_dwordx4 v[172:173], off sc1
	s_mov_b32 m0, s35
	s_nop 0
	global_load_lds_dwordx4 v[174:175], off sc1
	s_waitcnt lgkmcnt(0)
	v_mfma_f32_32x32x16_bf16 v[32:47], v[84:87], v[92:95], v[32:47]
	s_waitcnt vmcnt(8)
	s_waitcnt lgkmcnt(0)
	s_barrier
	v_mfma_f32_32x32x16_bf16 v[48:63], v[84:87], v[152:155], v[48:63]
	v_mfma_f32_32x32x16_bf16 v[0:15], v[88:91], v[92:95], v[0:15]
	v_mfma_f32_32x32x16_bf16 v[16:31], v[88:91], v[152:155], v[16:31]
	v_mfma_f32_32x32x16_bf16 v[32:47], v[156:159], v[164:167], v[32:47]
	v_mfma_f32_32x32x16_bf16 v[48:63], v[156:159], v[168:171], v[48:63]
	v_mfma_f32_32x32x16_bf16 v[0:15], v[160:163], v[164:167], v[0:15]
	v_mfma_f32_32x32x16_bf16 v[16:31], v[160:163], v[168:171], v[16:31]
	ds_read_b128 v[80:83], v68 offset:49152
	ds_read_b128 v[84:87], v68 offset:51200
	ds_read_b128 v[88:91], v69 offset:57344
	ds_read_b128 v[92:95], v69 offset:59392
	ds_read_b128 v[152:155], v70 offset:49152
	ds_read_b128 v[156:159], v70 offset:51200
	ds_read_b128 v[160:163], v71 offset:57344
	ds_read_b128 v[164:167], v71 offset:59392
	s_mov_b64 s[40:41], 0x24000
	s_mov_b64 s[36:37], 0x24400
	v_readfirstlane_b32 s42, v76
	v_lshl_add_u64 v[170:171], v[66:67], 0, s[36:37]
	v_lshl_add_u64 v[172:173], v[64:65], 0, s[36:37]
	v_lshl_add_u64 v[174:175], v[64:65], 0, s[40:41]
	s_mov_b32 m0, s42
	v_readfirstlane_b32 s36, v77
	global_load_lds_dwordx4 v[174:175], off sc1
	s_mov_b32 m0, s36
	v_readfirstlane_b32 s37, v78
	v_lshl_add_u64 v[168:169], v[66:67], 0, s[40:41]
	global_load_lds_dwordx4 v[172:173], off sc1
	s_mov_b32 m0, s37
	v_readfirstlane_b32 s39, v79
	global_load_lds_dwordx4 v[168:169], off sc1
	s_mov_b32 m0, s39
	s_nop 0
	global_load_lds_dwordx4 v[170:171], off sc1
	s_waitcnt lgkmcnt(0)
	v_mfma_f32_32x32x16_bf16 v[32:47], v[80:83], v[88:91], v[32:47]
	s_waitcnt vmcnt(8)
	s_waitcnt lgkmcnt(0)
	s_barrier
	v_mfma_f32_32x32x16_bf16 v[48:63], v[80:83], v[92:95], v[48:63]
	v_mfma_f32_32x32x16_bf16 v[0:15], v[84:87], v[88:91], v[0:15]
	v_mfma_f32_32x32x16_bf16 v[16:31], v[84:87], v[92:95], v[16:31]
	v_mfma_f32_32x32x16_bf16 v[32:47], v[152:155], v[160:163], v[32:47]
	v_mfma_f32_32x32x16_bf16 v[48:63], v[152:155], v[164:167], v[48:63]
	v_mfma_f32_32x32x16_bf16 v[0:15], v[156:159], v[160:163], v[0:15]
	v_mfma_f32_32x32x16_bf16 v[16:31], v[156:159], v[164:167], v[16:31]
	ds_read_b128 v[76:79], v68
	ds_read_b128 v[80:83], v68 offset:2048
	ds_read_b128 v[84:87], v69 offset:8192
	ds_read_b128 v[88:91], v69 offset:10240
	ds_read_b128 v[92:95], v70
	ds_read_b128 v[152:155], v70 offset:2048
	ds_read_b128 v[156:159], v71 offset:8192
	ds_read_b128 v[160:163], v71 offset:10240
	s_mov_b64 s[48:49], 0x26000
	v_lshl_add_u64 v[164:165], v[66:67], 0, s[48:49]
	s_mov_b64 s[40:41], 0x26400
	v_lshl_add_u64 v[170:171], v[64:65], 0, s[48:49]
	v_readfirstlane_b32 s48, v72
	v_lshl_add_u64 v[166:167], v[66:67], 0, s[40:41]
	v_lshl_add_u64 v[168:169], v[64:65], 0, s[40:41]
	s_mov_b32 m0, s48
	v_readfirstlane_b32 s40, v73
	global_load_lds_dwordx4 v[170:171], off sc1
	s_mov_b32 m0, s40
	v_readfirstlane_b32 s41, v74
	global_load_lds_dwordx4 v[168:169], off sc1
	s_mov_b32 m0, s41
	v_readfirstlane_b32 s43, v75
	global_load_lds_dwordx4 v[164:165], off sc1
	s_mov_b32 m0, s43
	s_nop 0
	global_load_lds_dwordx4 v[166:167], off sc1
	s_waitcnt lgkmcnt(0)
	v_mfma_f32_32x32x16_bf16 v[32:47], v[76:79], v[84:87], v[32:47]
	s_waitcnt vmcnt(8)
	s_waitcnt lgkmcnt(0)
	s_barrier
	v_mfma_f32_32x32x16_bf16 v[48:63], v[76:79], v[88:91], v[48:63]
	v_mfma_f32_32x32x16_bf16 v[0:15], v[80:83], v[84:87], v[0:15]
	v_mfma_f32_32x32x16_bf16 v[16:31], v[80:83], v[88:91], v[16:31]
	v_mfma_f32_32x32x16_bf16 v[32:47], v[92:95], v[156:159], v[32:47]
	v_mfma_f32_32x32x16_bf16 v[48:63], v[92:95], v[160:163], v[48:63]
	v_mfma_f32_32x32x16_bf16 v[0:15], v[152:155], v[156:159], v[0:15]
	v_mfma_f32_32x32x16_bf16 v[16:31], v[152:155], v[160:163], v[16:31]
	ds_read_b128 v[72:75], v68 offset:16384
	ds_read_b128 v[76:79], v68 offset:18432
	ds_read_b128 v[80:83], v69 offset:24576
	ds_read_b128 v[84:87], v69 offset:26624
	ds_read_b128 v[88:91], v70 offset:16384
	ds_read_b128 v[92:95], v70 offset:18432
	ds_read_b128 v[152:155], v71 offset:24576
	ds_read_b128 v[156:159], v71 offset:26624
	s_mov_b64 s[64:65], 0x28000
	s_mov_b32 m0, s34
	s_mov_b64 s[68:69], 0x28400
	v_lshl_add_u64 v[166:167], v[64:65], 0, s[64:65]
	v_lshl_add_u64 v[164:165], v[64:65], 0, s[68:69]
	global_load_lds_dwordx4 v[166:167], off sc1
	s_mov_b32 m0, s1
	v_lshl_add_u64 v[160:161], v[66:67], 0, s[64:65]
	global_load_lds_dwordx4 v[164:165], off sc1
	s_mov_b32 m0, s21
	v_lshl_add_u64 v[162:163], v[66:67], 0, s[68:69]
	global_load_lds_dwordx4 v[160:161], off sc1
	s_mov_b32 m0, s22
	s_nop 0
	global_load_lds_dwordx4 v[162:163], off sc1
	s_waitcnt lgkmcnt(0)
	v_mfma_f32_32x32x16_bf16 v[32:47], v[72:75], v[80:83], v[32:47]
	s_waitcnt vmcnt(8)
	s_waitcnt lgkmcnt(0)
	s_barrier
	v_mfma_f32_32x32x16_bf16 v[48:63], v[72:75], v[84:87], v[48:63]
	v_mfma_f32_32x32x16_bf16 v[0:15], v[76:79], v[80:83], v[0:15]
	v_mfma_f32_32x32x16_bf16 v[16:31], v[76:79], v[84:87], v[16:31]
	v_mfma_f32_32x32x16_bf16 v[32:47], v[88:91], v[152:155], v[32:47]
	v_mfma_f32_32x32x16_bf16 v[48:63], v[88:91], v[156:159], v[48:63]
	v_mfma_f32_32x32x16_bf16 v[0:15], v[92:95], v[152:155], v[0:15]
	v_mfma_f32_32x32x16_bf16 v[16:31], v[92:95], v[156:159], v[16:31]
	ds_read_b128 v[72:75], v68 offset:32768
	ds_read_b128 v[76:79], v68 offset:34816
	ds_read_b128 v[80:83], v69 offset:40960
	ds_read_b128 v[84:87], v69 offset:43008
	ds_read_b128 v[88:91], v70 offset:32768
	ds_read_b128 v[92:95], v70 offset:34816
	ds_read_b128 v[152:155], v71 offset:40960
	ds_read_b128 v[156:159], v71 offset:43008
	s_mov_b64 s[64:65], 0x2a000
	s_mov_b32 m0, s38
	s_mov_b64 s[68:69], 0x2a400
	v_lshl_add_u64 v[166:167], v[64:65], 0, s[64:65]
	v_lshl_add_u64 v[164:165], v[64:65], 0, s[68:69]
	global_load_lds_dwordx4 v[166:167], off sc1
	s_mov_b32 m0, s23
	v_lshl_add_u64 v[160:161], v[66:67], 0, s[64:65]
	global_load_lds_dwordx4 v[164:165], off sc1
	s_mov_b32 m0, s30
	v_lshl_add_u64 v[162:163], v[66:67], 0, s[68:69]
	global_load_lds_dwordx4 v[160:161], off sc1
	s_mov_b32 m0, s35
	s_nop 0
	global_load_lds_dwordx4 v[162:163], off sc1
	s_waitcnt lgkmcnt(0)
	v_mfma_f32_32x32x16_bf16 v[32:47], v[72:75], v[80:83], v[32:47]
	s_waitcnt vmcnt(8)
	s_waitcnt lgkmcnt(0)
	s_barrier
	v_mfma_f32_32x32x16_bf16 v[48:63], v[72:75], v[84:87], v[48:63]
	v_mfma_f32_32x32x16_bf16 v[0:15], v[76:79], v[80:83], v[0:15]
	v_mfma_f32_32x32x16_bf16 v[16:31], v[76:79], v[84:87], v[16:31]
	v_mfma_f32_32x32x16_bf16 v[32:47], v[88:91], v[152:155], v[32:47]
	v_mfma_f32_32x32x16_bf16 v[48:63], v[88:91], v[156:159], v[48:63]
	v_mfma_f32_32x32x16_bf16 v[0:15], v[92:95], v[152:155], v[0:15]
	v_mfma_f32_32x32x16_bf16 v[16:31], v[92:95], v[156:159], v[16:31]
	ds_read_b128 v[72:75], v68 offset:49152
	ds_read_b128 v[76:79], v68 offset:51200
	ds_read_b128 v[80:83], v69 offset:57344
	ds_read_b128 v[84:87], v69 offset:59392
	ds_read_b128 v[88:91], v70 offset:49152
	ds_read_b128 v[92:95], v70 offset:51200
	ds_read_b128 v[152:155], v71 offset:57344
	ds_read_b128 v[156:159], v71 offset:59392
	s_mov_b64 s[64:65], 0x2c000
	s_mov_b32 m0, s42
	s_mov_b64 s[68:69], 0x2c400
	v_lshl_add_u64 v[166:167], v[64:65], 0, s[64:65]
	v_lshl_add_u64 v[164:165], v[64:65], 0, s[68:69]
	global_load_lds_dwordx4 v[166:167], off sc1
	s_mov_b32 m0, s36
	v_lshl_add_u64 v[160:161], v[66:67], 0, s[64:65]
	global_load_lds_dwordx4 v[164:165], off sc1
	s_mov_b32 m0, s37
	v_lshl_add_u64 v[162:163], v[66:67], 0, s[68:69]
	global_load_lds_dwordx4 v[160:161], off sc1
	s_mov_b32 m0, s39
	s_nop 0
	global_load_lds_dwordx4 v[162:163], off sc1
	s_waitcnt lgkmcnt(0)
	v_mfma_f32_32x32x16_bf16 v[32:47], v[72:75], v[80:83], v[32:47]
	s_waitcnt vmcnt(8)
	s_waitcnt lgkmcnt(0)
	s_barrier
	v_mfma_f32_32x32x16_bf16 v[48:63], v[72:75], v[84:87], v[48:63]
	v_mfma_f32_32x32x16_bf16 v[0:15], v[76:79], v[80:83], v[0:15]
	v_mfma_f32_32x32x16_bf16 v[16:31], v[76:79], v[84:87], v[16:31]
	v_mfma_f32_32x32x16_bf16 v[32:47], v[88:91], v[152:155], v[32:47]
	v_mfma_f32_32x32x16_bf16 v[48:63], v[88:91], v[156:159], v[48:63]
	v_mfma_f32_32x32x16_bf16 v[0:15], v[92:95], v[152:155], v[0:15]
	v_mfma_f32_32x32x16_bf16 v[16:31], v[92:95], v[156:159], v[16:31]
	ds_read_b128 v[72:75], v68
	ds_read_b128 v[76:79], v68 offset:2048
	ds_read_b128 v[80:83], v69 offset:8192
	ds_read_b128 v[84:87], v69 offset:10240
	ds_read_b128 v[88:91], v70
	ds_read_b128 v[92:95], v70 offset:2048
	ds_read_b128 v[152:155], v71 offset:8192
	ds_read_b128 v[156:159], v71 offset:10240
	s_mov_b64 s[64:65], 0x2e000
	s_mov_b32 m0, s48
	s_mov_b64 s[68:69], 0x2e400
	v_lshl_add_u64 v[166:167], v[64:65], 0, s[64:65]
	v_lshl_add_u64 v[164:165], v[64:65], 0, s[68:69]
	global_load_lds_dwordx4 v[166:167], off sc1
	s_mov_b32 m0, s40
	v_lshl_add_u64 v[160:161], v[66:67], 0, s[64:65]
	global_load_lds_dwordx4 v[164:165], off sc1
	s_mov_b32 m0, s41
	v_lshl_add_u64 v[162:163], v[66:67], 0, s[68:69]
	global_load_lds_dwordx4 v[160:161], off sc1
	s_mov_b32 m0, s43
	s_nop 0
	global_load_lds_dwordx4 v[162:163], off sc1
	s_waitcnt lgkmcnt(0)
	v_mfma_f32_32x32x16_bf16 v[32:47], v[72:75], v[80:83], v[32:47]
	s_waitcnt vmcnt(8)
	s_waitcnt lgkmcnt(0)
	s_barrier
	v_mfma_f32_32x32x16_bf16 v[48:63], v[72:75], v[84:87], v[48:63]
	v_mfma_f32_32x32x16_bf16 v[0:15], v[76:79], v[80:83], v[0:15]
	v_mfma_f32_32x32x16_bf16 v[16:31], v[76:79], v[84:87], v[16:31]
	v_mfma_f32_32x32x16_bf16 v[32:47], v[88:91], v[152:155], v[32:47]
	v_mfma_f32_32x32x16_bf16 v[48:63], v[88:91], v[156:159], v[48:63]
	v_mfma_f32_32x32x16_bf16 v[0:15], v[92:95], v[152:155], v[0:15]
	v_mfma_f32_32x32x16_bf16 v[16:31], v[92:95], v[156:159], v[16:31]
	ds_read_b128 v[72:75], v68 offset:16384
	ds_read_b128 v[76:79], v68 offset:18432
	ds_read_b128 v[80:83], v69 offset:24576
	ds_read_b128 v[84:87], v69 offset:26624
	ds_read_b128 v[88:91], v70 offset:16384
	ds_read_b128 v[92:95], v70 offset:18432
	ds_read_b128 v[152:155], v71 offset:24576
	ds_read_b128 v[156:159], v71 offset:26624
	s_mov_b64 s[64:65], 0x30000
	s_mov_b32 m0, s34
	s_mov_b64 s[68:69], 0x30400
	v_lshl_add_u64 v[166:167], v[64:65], 0, s[64:65]
	v_lshl_add_u64 v[164:165], v[64:65], 0, s[68:69]
	global_load_lds_dwordx4 v[166:167], off sc1
	s_mov_b32 m0, s1
	v_lshl_add_u64 v[160:161], v[66:67], 0, s[64:65]
	global_load_lds_dwordx4 v[164:165], off sc1
	s_mov_b32 m0, s21
	v_lshl_add_u64 v[162:163], v[66:67], 0, s[68:69]
	global_load_lds_dwordx4 v[160:161], off sc1
	s_mov_b32 m0, s22
	s_nop 0
	global_load_lds_dwordx4 v[162:163], off sc1
	s_waitcnt lgkmcnt(0)
	v_mfma_f32_32x32x16_bf16 v[32:47], v[72:75], v[80:83], v[32:47]
	s_waitcnt vmcnt(8)
	s_waitcnt lgkmcnt(0)
	s_barrier
	v_mfma_f32_32x32x16_bf16 v[48:63], v[72:75], v[84:87], v[48:63]
	v_mfma_f32_32x32x16_bf16 v[0:15], v[76:79], v[80:83], v[0:15]
	v_mfma_f32_32x32x16_bf16 v[16:31], v[76:79], v[84:87], v[16:31]
	v_mfma_f32_32x32x16_bf16 v[32:47], v[88:91], v[152:155], v[32:47]
	v_mfma_f32_32x32x16_bf16 v[48:63], v[88:91], v[156:159], v[48:63]
	v_mfma_f32_32x32x16_bf16 v[0:15], v[92:95], v[152:155], v[0:15]
	v_mfma_f32_32x32x16_bf16 v[16:31], v[92:95], v[156:159], v[16:31]
	ds_read_b128 v[72:75], v68 offset:32768
	ds_read_b128 v[76:79], v68 offset:34816
	ds_read_b128 v[80:83], v69 offset:40960
	ds_read_b128 v[84:87], v69 offset:43008
	ds_read_b128 v[88:91], v70 offset:32768
	ds_read_b128 v[92:95], v70 offset:34816
	ds_read_b128 v[152:155], v71 offset:40960
	ds_read_b128 v[156:159], v71 offset:43008
	s_mov_b64 s[64:65], 0x32000
	s_mov_b32 m0, s38
	s_mov_b64 s[68:69], 0x32400
	v_lshl_add_u64 v[166:167], v[64:65], 0, s[64:65]
	v_lshl_add_u64 v[164:165], v[64:65], 0, s[68:69]
	global_load_lds_dwordx4 v[166:167], off sc1
	s_mov_b32 m0, s23
	v_lshl_add_u64 v[160:161], v[66:67], 0, s[64:65]
	global_load_lds_dwordx4 v[164:165], off sc1
	s_mov_b32 m0, s30
	v_lshl_add_u64 v[162:163], v[66:67], 0, s[68:69]
	global_load_lds_dwordx4 v[160:161], off sc1
	s_mov_b32 m0, s35
	s_nop 0
	global_load_lds_dwordx4 v[162:163], off sc1
	s_waitcnt lgkmcnt(0)
	v_mfma_f32_32x32x16_bf16 v[32:47], v[72:75], v[80:83], v[32:47]
	s_waitcnt vmcnt(8)
	s_waitcnt lgkmcnt(0)
	s_barrier
	v_mfma_f32_32x32x16_bf16 v[48:63], v[72:75], v[84:87], v[48:63]
	v_mfma_f32_32x32x16_bf16 v[0:15], v[76:79], v[80:83], v[0:15]
	v_mfma_f32_32x32x16_bf16 v[16:31], v[76:79], v[84:87], v[16:31]
	v_mfma_f32_32x32x16_bf16 v[32:47], v[88:91], v[152:155], v[32:47]
	v_mfma_f32_32x32x16_bf16 v[48:63], v[88:91], v[156:159], v[48:63]
	v_mfma_f32_32x32x16_bf16 v[0:15], v[92:95], v[152:155], v[0:15]
	v_mfma_f32_32x32x16_bf16 v[16:31], v[92:95], v[156:159], v[16:31]
	ds_read_b128 v[72:75], v68 offset:49152
	ds_read_b128 v[76:79], v68 offset:51200
	ds_read_b128 v[80:83], v69 offset:57344
	ds_read_b128 v[84:87], v69 offset:59392
	ds_read_b128 v[88:91], v70 offset:49152
	ds_read_b128 v[92:95], v70 offset:51200
	ds_read_b128 v[152:155], v71 offset:57344
	ds_read_b128 v[156:159], v71 offset:59392
	s_mov_b64 s[64:65], 0x34000
	s_mov_b32 m0, s42
	s_mov_b64 s[68:69], 0x34400
	v_lshl_add_u64 v[166:167], v[64:65], 0, s[64:65]
	v_lshl_add_u64 v[164:165], v[64:65], 0, s[68:69]
	global_load_lds_dwordx4 v[166:167], off sc1
	s_mov_b32 m0, s36
	v_lshl_add_u64 v[160:161], v[66:67], 0, s[64:65]
	global_load_lds_dwordx4 v[164:165], off sc1
	s_mov_b32 m0, s37
	v_lshl_add_u64 v[162:163], v[66:67], 0, s[68:69]
	global_load_lds_dwordx4 v[160:161], off sc1
	s_mov_b32 m0, s39
	s_nop 0
	global_load_lds_dwordx4 v[162:163], off sc1
	s_waitcnt lgkmcnt(0)
	v_mfma_f32_32x32x16_bf16 v[32:47], v[72:75], v[80:83], v[32:47]
	s_waitcnt vmcnt(8)
	s_waitcnt lgkmcnt(0)
	s_barrier
	v_mfma_f32_32x32x16_bf16 v[48:63], v[72:75], v[84:87], v[48:63]
	v_mfma_f32_32x32x16_bf16 v[0:15], v[76:79], v[80:83], v[0:15]
	v_mfma_f32_32x32x16_bf16 v[16:31], v[76:79], v[84:87], v[16:31]
	v_mfma_f32_32x32x16_bf16 v[32:47], v[88:91], v[152:155], v[32:47]
	v_mfma_f32_32x32x16_bf16 v[48:63], v[88:91], v[156:159], v[48:63]
	v_mfma_f32_32x32x16_bf16 v[0:15], v[92:95], v[152:155], v[0:15]
	v_mfma_f32_32x32x16_bf16 v[16:31], v[92:95], v[156:159], v[16:31]
	ds_read_b128 v[72:75], v68
	ds_read_b128 v[76:79], v68 offset:2048
	ds_read_b128 v[80:83], v69 offset:8192
	ds_read_b128 v[84:87], v69 offset:10240
	ds_read_b128 v[88:91], v70
	ds_read_b128 v[92:95], v70 offset:2048
	ds_read_b128 v[152:155], v71 offset:8192
	ds_read_b128 v[156:159], v71 offset:10240
	s_mov_b64 s[64:65], 0x36000
	s_mov_b32 m0, s48
	s_mov_b64 s[68:69], 0x36400
	v_lshl_add_u64 v[166:167], v[64:65], 0, s[64:65]
	v_lshl_add_u64 v[164:165], v[64:65], 0, s[68:69]
	global_load_lds_dwordx4 v[166:167], off sc1
	s_mov_b32 m0, s40
	v_lshl_add_u64 v[160:161], v[66:67], 0, s[64:65]
	global_load_lds_dwordx4 v[164:165], off sc1
	s_mov_b32 m0, s41
	v_lshl_add_u64 v[162:163], v[66:67], 0, s[68:69]
	global_load_lds_dwordx4 v[160:161], off sc1
	s_mov_b32 m0, s43
	s_nop 0
	global_load_lds_dwordx4 v[162:163], off sc1
	s_waitcnt lgkmcnt(0)
	v_mfma_f32_32x32x16_bf16 v[32:47], v[72:75], v[80:83], v[32:47]
	s_waitcnt vmcnt(8)
	s_waitcnt lgkmcnt(0)
	s_barrier
	v_mfma_f32_32x32x16_bf16 v[48:63], v[72:75], v[84:87], v[48:63]
	v_mfma_f32_32x32x16_bf16 v[0:15], v[76:79], v[80:83], v[0:15]
	v_mfma_f32_32x32x16_bf16 v[16:31], v[76:79], v[84:87], v[16:31]
	v_mfma_f32_32x32x16_bf16 v[32:47], v[88:91], v[152:155], v[32:47]
	v_mfma_f32_32x32x16_bf16 v[48:63], v[88:91], v[156:159], v[48:63]
	v_mfma_f32_32x32x16_bf16 v[0:15], v[92:95], v[152:155], v[0:15]
	v_mfma_f32_32x32x16_bf16 v[16:31], v[92:95], v[156:159], v[16:31]
	ds_read_b128 v[72:75], v68 offset:16384
	ds_read_b128 v[76:79], v68 offset:18432
	ds_read_b128 v[80:83], v69 offset:24576
	ds_read_b128 v[84:87], v69 offset:26624
	ds_read_b128 v[88:91], v70 offset:16384
	ds_read_b128 v[92:95], v70 offset:18432
	ds_read_b128 v[152:155], v71 offset:24576
	ds_read_b128 v[156:159], v71 offset:26624
	s_mov_b64 s[64:65], 0x38000
	s_mov_b32 m0, s34
	s_mov_b64 s[68:69], 0x38400
	v_lshl_add_u64 v[166:167], v[64:65], 0, s[64:65]
	v_lshl_add_u64 v[164:165], v[64:65], 0, s[68:69]
	global_load_lds_dwordx4 v[166:167], off sc1
	s_mov_b32 m0, s1
	v_lshl_add_u64 v[160:161], v[66:67], 0, s[64:65]
	global_load_lds_dwordx4 v[164:165], off sc1
	s_mov_b32 m0, s21
	v_lshl_add_u64 v[162:163], v[66:67], 0, s[68:69]
	global_load_lds_dwordx4 v[160:161], off sc1
	s_mov_b32 m0, s22
	s_nop 0
	global_load_lds_dwordx4 v[162:163], off sc1
	s_waitcnt lgkmcnt(0)
	v_mfma_f32_32x32x16_bf16 v[32:47], v[72:75], v[80:83], v[32:47]
	s_waitcnt vmcnt(8)
	s_waitcnt lgkmcnt(0)
	s_barrier
	v_mfma_f32_32x32x16_bf16 v[48:63], v[72:75], v[84:87], v[48:63]
	v_mfma_f32_32x32x16_bf16 v[0:15], v[76:79], v[80:83], v[0:15]
	v_mfma_f32_32x32x16_bf16 v[16:31], v[76:79], v[84:87], v[16:31]
	v_mfma_f32_32x32x16_bf16 v[32:47], v[88:91], v[152:155], v[32:47]
	v_mfma_f32_32x32x16_bf16 v[48:63], v[88:91], v[156:159], v[48:63]
	v_mfma_f32_32x32x16_bf16 v[0:15], v[92:95], v[152:155], v[0:15]
	v_mfma_f32_32x32x16_bf16 v[16:31], v[92:95], v[156:159], v[16:31]
	ds_read_b128 v[72:75], v68 offset:32768
	ds_read_b128 v[76:79], v68 offset:34816
	ds_read_b128 v[80:83], v69 offset:40960
	ds_read_b128 v[84:87], v69 offset:43008
	ds_read_b128 v[88:91], v70 offset:32768
	ds_read_b128 v[92:95], v70 offset:34816
	ds_read_b128 v[152:155], v71 offset:40960
	ds_read_b128 v[156:159], v71 offset:43008
	s_mov_b64 s[64:65], 0x3a000
	s_mov_b32 m0, s38
	s_mov_b64 s[68:69], 0x3a400
	v_lshl_add_u64 v[166:167], v[64:65], 0, s[64:65]
	v_lshl_add_u64 v[164:165], v[64:65], 0, s[68:69]
	global_load_lds_dwordx4 v[166:167], off sc1
	s_mov_b32 m0, s23
	v_lshl_add_u64 v[160:161], v[66:67], 0, s[64:65]
	global_load_lds_dwordx4 v[164:165], off sc1
	s_mov_b32 m0, s30
	v_lshl_add_u64 v[162:163], v[66:67], 0, s[68:69]
	global_load_lds_dwordx4 v[160:161], off sc1
	s_mov_b32 m0, s35
	s_nop 0
	global_load_lds_dwordx4 v[162:163], off sc1
	s_waitcnt lgkmcnt(0)
	v_mfma_f32_32x32x16_bf16 v[32:47], v[72:75], v[80:83], v[32:47]
	s_waitcnt vmcnt(8)
	s_waitcnt lgkmcnt(0)
	s_barrier
	v_mfma_f32_32x32x16_bf16 v[48:63], v[72:75], v[84:87], v[48:63]
	v_mfma_f32_32x32x16_bf16 v[0:15], v[76:79], v[80:83], v[0:15]
	v_mfma_f32_32x32x16_bf16 v[16:31], v[76:79], v[84:87], v[16:31]
	v_mfma_f32_32x32x16_bf16 v[32:47], v[88:91], v[152:155], v[32:47]
	v_mfma_f32_32x32x16_bf16 v[48:63], v[88:91], v[156:159], v[48:63]
	v_mfma_f32_32x32x16_bf16 v[0:15], v[92:95], v[152:155], v[0:15]
	v_mfma_f32_32x32x16_bf16 v[16:31], v[92:95], v[156:159], v[16:31]
	ds_read_b128 v[72:75], v68 offset:49152
	ds_read_b128 v[76:79], v68 offset:51200
	ds_read_b128 v[80:83], v69 offset:57344
	ds_read_b128 v[84:87], v69 offset:59392
	ds_read_b128 v[88:91], v70 offset:49152
	ds_read_b128 v[92:95], v70 offset:51200
	ds_read_b128 v[152:155], v71 offset:57344
	ds_read_b128 v[156:159], v71 offset:59392
	s_mov_b64 s[22:23], 0x3c000
	s_mov_b32 m0, s42
	s_mov_b64 s[34:35], 0x3c400
	v_lshl_add_u64 v[166:167], v[64:65], 0, s[22:23]
	v_lshl_add_u64 v[164:165], v[64:65], 0, s[34:35]
	global_load_lds_dwordx4 v[166:167], off sc1
	s_mov_b32 m0, s36
	v_lshl_add_u64 v[160:161], v[66:67], 0, s[22:23]
	global_load_lds_dwordx4 v[164:165], off sc1
	s_mov_b32 m0, s37
	v_lshl_add_u64 v[162:163], v[66:67], 0, s[34:35]
	global_load_lds_dwordx4 v[160:161], off sc1
	s_mov_b32 m0, s39
	s_nop 0
	global_load_lds_dwordx4 v[162:163], off sc1
	s_waitcnt lgkmcnt(0)
	v_mfma_f32_32x32x16_bf16 v[32:47], v[72:75], v[80:83], v[32:47]
	s_waitcnt vmcnt(8)
	s_waitcnt lgkmcnt(0)
	s_barrier
	v_mfma_f32_32x32x16_bf16 v[48:63], v[72:75], v[84:87], v[48:63]
	v_mfma_f32_32x32x16_bf16 v[0:15], v[76:79], v[80:83], v[0:15]
	v_mfma_f32_32x32x16_bf16 v[16:31], v[76:79], v[84:87], v[16:31]
	v_mfma_f32_32x32x16_bf16 v[32:47], v[88:91], v[152:155], v[32:47]
	v_mfma_f32_32x32x16_bf16 v[48:63], v[88:91], v[156:159], v[48:63]
	v_mfma_f32_32x32x16_bf16 v[0:15], v[92:95], v[152:155], v[0:15]
	v_mfma_f32_32x32x16_bf16 v[16:31], v[92:95], v[156:159], v[16:31]
	ds_read_b128 v[72:75], v68
	ds_read_b128 v[76:79], v68 offset:2048
	ds_read_b128 v[80:83], v69 offset:8192
	ds_read_b128 v[84:87], v69 offset:10240
	ds_read_b128 v[88:91], v70
	ds_read_b128 v[92:95], v70 offset:2048
	ds_read_b128 v[152:155], v71 offset:8192
	ds_read_b128 v[156:159], v71 offset:10240
	s_mov_b64 s[22:23], 0x3e000
	s_mov_b64 s[34:35], 0x3e400
	s_mov_b32 m0, s48
	v_lshl_add_u64 v[162:163], v[64:65], 0, s[34:35]
	v_lshl_add_u64 v[64:65], v[64:65], 0, s[22:23]
	global_load_lds_dwordx4 v[64:65], off sc1
	s_mov_b32 m0, s40
	v_lshl_add_u64 v[160:161], v[66:67], 0, s[22:23]
	global_load_lds_dwordx4 v[162:163], off sc1
	s_mov_b32 m0, s41
	v_lshl_add_u64 v[66:67], v[66:67], 0, s[34:35]
	global_load_lds_dwordx4 v[160:161], off sc1
	s_mov_b32 m0, s43
	s_nop 0
	global_load_lds_dwordx4 v[66:67], off sc1
	s_waitcnt lgkmcnt(0)
	v_mfma_f32_32x32x16_bf16 v[32:47], v[72:75], v[80:83], v[32:47]
	s_waitcnt vmcnt(8)
	s_waitcnt lgkmcnt(0)
	s_barrier
	v_mfma_f32_32x32x16_bf16 v[48:63], v[72:75], v[84:87], v[48:63]
	v_mfma_f32_32x32x16_bf16 v[0:15], v[76:79], v[80:83], v[0:15]
	v_mfma_f32_32x32x16_bf16 v[16:31], v[76:79], v[84:87], v[16:31]
	v_mfma_f32_32x32x16_bf16 v[32:47], v[88:91], v[152:155], v[32:47]
	v_mfma_f32_32x32x16_bf16 v[48:63], v[88:91], v[156:159], v[48:63]
	v_mfma_f32_32x32x16_bf16 v[0:15], v[92:95], v[152:155], v[0:15]
	v_mfma_f32_32x32x16_bf16 v[16:31], v[92:95], v[156:159], v[16:31]
	ds_read_b128 v[64:67], v68 offset:16384
	ds_read_b128 v[72:75], v68 offset:18432
	ds_read_b128 v[76:79], v69 offset:24576
	ds_read_b128 v[80:83], v69 offset:26624
	ds_read_b128 v[84:87], v70 offset:16384
	ds_read_b128 v[88:91], v70 offset:18432
	ds_read_b128 v[92:95], v71 offset:24576
	ds_read_b128 v[152:155], v71 offset:26624
	s_waitcnt lgkmcnt(0)
	v_mfma_f32_32x32x16_bf16 v[32:47], v[64:67], v[76:79], v[32:47]
	s_waitcnt vmcnt(4)
	s_waitcnt lgkmcnt(0)
	s_barrier
	v_mfma_f32_32x32x16_bf16 v[48:63], v[64:67], v[80:83], v[48:63]
	v_mfma_f32_32x32x16_bf16 v[0:15], v[72:75], v[76:79], v[0:15]
	v_mfma_f32_32x32x16_bf16 v[16:31], v[72:75], v[80:83], v[16:31]
	v_mfma_f32_32x32x16_bf16 v[32:47], v[84:87], v[92:95], v[32:47]
	v_mfma_f32_32x32x16_bf16 v[48:63], v[84:87], v[152:155], v[48:63]
	v_mfma_f32_32x32x16_bf16 v[0:15], v[88:91], v[92:95], v[0:15]
	v_mfma_f32_32x32x16_bf16 v[16:31], v[88:91], v[152:155], v[16:31]
	ds_read_b128 v[64:67], v68 offset:32768
	ds_read_b128 v[72:75], v68 offset:34816
	ds_read_b128 v[76:79], v69 offset:40960
	ds_read_b128 v[80:83], v69 offset:43008
	ds_read_b128 v[84:87], v70 offset:32768
	ds_read_b128 v[88:91], v70 offset:34816
	ds_read_b128 v[92:95], v71 offset:40960
	ds_read_b128 v[152:155], v71 offset:43008
	s_waitcnt lgkmcnt(0)
	v_mfma_f32_32x32x16_bf16 v[32:47], v[64:67], v[76:79], v[32:47]
	s_waitcnt vmcnt(0)
	s_waitcnt lgkmcnt(0)
	s_barrier
	v_mfma_f32_32x32x16_bf16 v[48:63], v[64:67], v[80:83], v[48:63]
	v_mfma_f32_32x32x16_bf16 v[0:15], v[72:75], v[76:79], v[0:15]
	v_mfma_f32_32x32x16_bf16 v[16:31], v[72:75], v[80:83], v[16:31]
	v_mfma_f32_32x32x16_bf16 v[32:47], v[84:87], v[92:95], v[32:47]
	v_mfma_f32_32x32x16_bf16 v[48:63], v[84:87], v[152:155], v[48:63]
	v_mfma_f32_32x32x16_bf16 v[0:15], v[88:91], v[92:95], v[0:15]
	v_mfma_f32_32x32x16_bf16 v[16:31], v[88:91], v[152:155], v[16:31]
	ds_read_b128 v[64:67], v68 offset:49152
	ds_read_b128 v[72:75], v68 offset:51200
	ds_read_b128 v[76:79], v69 offset:57344
	ds_read_b128 v[80:83], v69 offset:59392
	ds_read_b128 v[84:87], v70 offset:49152
	ds_read_b128 v[88:91], v70 offset:51200
	ds_read_b128 v[92:95], v71 offset:57344
	ds_read_b128 v[68:71], v71 offset:59392
	s_lshl_b32 s21, s0, 7
	s_add_i32 s1, s21, 0xfffff000
	s_lshr_b32 s1, s1, 10
	s_add_i32 s1, s1, 1
	s_cmp_gt_i32 s0, 31
	s_cselect_b32 s0, s1, 0
	s_mul_i32 s1, s12, 3
	s_add_i32 s0, s0, s1
	s_waitcnt lgkmcnt(0)
	v_mfma_f32_32x32x16_bf16 v[48:63], v[64:67], v[80:83], v[48:63]
	s_mul_hi_u32 s1, s0, 0x6000
	s_mulk_i32 s0, 0x6000
	s_add_u32 s22, s16, s0
	s_addc_u32 s23, s17, s1
	s_movk_i32 s0, 0x2000
	s_lshl_b32 s30, s20, 2
	s_waitcnt lgkmcnt(0)
	v_mfma_f32_32x32x16_bf16 v[16:31], v[72:75], v[80:83], v[16:31]
	s_barrier
	v_add_u32_e32 v186, s21, v191
	v_ashrrev_i32_e32 v187, 31, v186
	v_lshl_add_u64 v[156:157], v[102:103], 0, s[30:31]
	v_lshlrev_b64 v[188:189], 12, v[186:187]
	v_add_u32_e32 v182, s21, v192
	v_ashrrev_i32_e32 v183, 31, v182
	v_mfma_f32_32x32x16_bf16 v[32:47], v[64:67], v[76:79], v[32:47]
	v_or_b32_e32 v64, s20, v190
	v_lshlrev_b32_e32 v64, 2, v64
	v_mov_b32_e32 v65, v117
	v_lshl_add_u64 v[64:65], s[22:23], 0, v[64:65]
	v_lshl_add_u64 v[66:67], v[64:65], 0, s[44:45]
	v_add_co_u32_e64 v64, s[0:1], s0, v64
	v_mfma_f32_32x32x16_bf16 v[48:63], v[84:87], v[68:71], v[48:63]
	s_nop 0
	v_addc_co_u32_e64 v65, s[0:1], 0, v65, s[0:1]
	s_add_u32 s0, s22, s30
	s_addc_u32 s1, s23, 0
	global_load_dword v137, v[64:65], off
	global_load_dword v139, v[66:67], off offset:128
	v_lshl_add_u64 v[64:65], v[104:105], 0, s[30:31]
	global_load_dwordx4 v[64:67], v[64:65], off sc1
	v_mfma_f32_32x32x16_bf16 v[16:31], v[88:91], v[68:71], v[16:31]
	v_lshl_add_u64 v[68:69], s[0:1], 0, v[116:117]
	s_movk_i32 s0, 0x4000
	v_add_co_u32_e64 v68, s[0:1], s0, v68
	v_add_u32_e32 v178, s21, v193
	s_nop 0
	v_addc_co_u32_e64 v69, s[0:1], 0, v69, s[0:1]
	global_load_dwordx4 v[68:71], v[68:69], off sc1
	v_mfma_f32_32x32x16_bf16 v[0:15], v[72:75], v[76:79], v[0:15]
	v_lshlrev_b64 v[184:185], 12, v[182:183]
	v_ashrrev_i32_e32 v179, 31, v178
	v_add_u32_e32 v174, s21, v194
	v_lshlrev_b64 v[180:181], 12, v[178:179]
	v_ashrrev_i32_e32 v175, 31, v174
	v_add_u32_e32 v170, s21, v195
	v_lshlrev_b64 v[176:177], 12, v[174:175]
	v_mfma_f32_32x32x16_bf16 v[32:47], v[84:87], v[92:95], v[32:47]
	v_ashrrev_i32_e32 v171, 31, v170
	v_add_u32_e32 v166, s21, v196
	v_lshlrev_b64 v[172:173], 12, v[170:171]
	v_ashrrev_i32_e32 v167, 31, v166
	v_add_u32_e32 v162, s21, v197
	v_lshlrev_b64 v[168:169], 12, v[166:167]
	v_ashrrev_i32_e32 v163, 31, v162
	v_mfma_f32_32x32x16_bf16 v[0:15], v[88:91], v[92:95], v[0:15]
	v_add_u32_e32 v158, s21, v198
	v_lshlrev_b64 v[164:165], 12, v[162:163]
	v_ashrrev_i32_e32 v159, 31, v158
	v_lshlrev_b64 v[160:161], 12, v[158:159]
	v_add_u32_e32 v141, 0x400, v199
	v_add_u32_e32 v143, 0x1000, v199
	v_add_u32_e32 v145, 0x1400, v199
	v_add_u32_e32 v147, 0x2000, v199
	v_add_u32_e32 v149, 0x2400, v199
	v_add_u32_e32 v151, 0x3000, v199
	v_add_u32_e32 v209, 0x3200, v199
	v_add_u32_e32 v210, 0x3400, v199
	v_add_u32_e32 v211, 0x3600, v199
	v_mov_b32_e32 v107, v117
	v_mov_b32_e32 v109, v117
	s_waitcnt vmcnt(0)
	v_mul_f32_e32 v32, v32, v137
	v_mul_f32_e32 v48, v48, v139
	ds_write2_b32 v199, v32, v48 offset1:32
	v_mul_f32_e32 v32, v33, v137
	v_mul_f32_e32 v33, v49, v139
	ds_write2_b32 v199, v32, v33 offset0:132 offset1:164
	v_mul_f32_e32 v32, v34, v137
	v_mul_f32_e32 v33, v50, v139
	ds_write2_b32 v141, v32, v33 offset0:8 offset1:40
	v_mul_f32_e32 v32, v35, v137
	v_mul_f32_e32 v33, v51, v139
	ds_write2_b32 v141, v32, v33 offset0:140 offset1:172
	v_pk_add_f32 v[68:69], v[68:69], 1.0 op_sel_hi:[1,0]
	v_pk_add_f32 v[70:71], v[70:71], 1.0 op_sel_hi:[1,0]
	v_pk_mul_f32 v[152:153], v[64:65], v[68:69]
	v_lshl_add_u64 v[64:65], v[156:157], 0, v[188:189]
	global_load_dwordx4 v[92:95], v[64:65], off sc1
	v_lshl_add_u64 v[64:65], v[156:157], 0, v[184:185]
	global_load_dwordx4 v[88:91], v[64:65], off sc1
	v_lshl_add_u64 v[64:65], v[156:157], 0, v[180:181]
	global_load_dwordx4 v[84:87], v[64:65], off sc1
	v_lshl_add_u64 v[64:65], v[156:157], 0, v[176:177]
	global_load_dwordx4 v[80:83], v[64:65], off sc1
	v_lshl_add_u64 v[64:65], v[156:157], 0, v[172:173]
	global_load_dwordx4 v[76:79], v[64:65], off sc1
	v_lshl_add_u64 v[64:65], v[156:157], 0, v[168:169]
	global_load_dwordx4 v[72:75], v[64:65], off sc1
	v_lshl_add_u64 v[64:65], v[156:157], 0, v[164:165]
	v_pk_mul_f32 v[154:155], v[66:67], v[70:71]
	global_load_dwordx4 v[68:71], v[64:65], off sc1
	v_lshl_add_u64 v[64:65], v[156:157], 0, v[160:161]
	global_load_dwordx4 v[64:67], v[64:65], off sc1
	v_mul_f32_e32 v32, v36, v137
	v_mul_f32_e32 v33, v52, v139
	ds_write2_b32 v143, v32, v33 offset0:32 offset1:64
	v_mul_f32_e32 v32, v37, v137
	v_mul_f32_e32 v33, v53, v139
	ds_write2_b32 v143, v32, v33 offset0:164 offset1:196
	v_mul_f32_e32 v32, v38, v137
	v_mul_f32_e32 v33, v54, v139
	ds_write2_b32 v145, v32, v33 offset0:40 offset1:72
	v_mul_f32_e32 v32, v39, v137
	v_mul_f32_e32 v33, v55, v139
	ds_write2_b32 v145, v32, v33 offset0:172 offset1:204
	v_mul_f32_e32 v32, v40, v137
	v_mul_f32_e32 v33, v56, v139
	ds_write2_b32 v147, v32, v33 offset0:64 offset1:96
	v_mul_f32_e32 v32, v41, v137
	v_mul_f32_e32 v33, v57, v139
	ds_write2_b32 v147, v32, v33 offset0:196 offset1:228
	v_mul_f32_e32 v32, v42, v137
	v_mul_f32_e32 v33, v58, v139
	ds_write2_b32 v149, v32, v33 offset0:72 offset1:104
	v_mul_f32_e32 v32, v43, v137
	v_mul_f32_e32 v33, v59, v139
	ds_write2_b32 v149, v32, v33 offset0:204 offset1:236
	v_mul_f32_e32 v32, v44, v137
	v_mul_f32_e32 v33, v60, v139
	ds_write2_b32 v151, v32, v33 offset0:96 offset1:128
	v_mul_f32_e32 v32, v45, v137
	v_mul_f32_e32 v33, v61, v139
	ds_write2_b32 v209, v32, v33 offset0:100 offset1:132
	v_mul_f32_e32 v32, v46, v137
	v_mul_f32_e32 v33, v62, v139
	ds_write2_b32 v210, v32, v33 offset0:104 offset1:136
	v_mul_f32_e32 v32, v47, v137
	v_mul_f32_e32 v33, v63, v139
	ds_write2_b32 v211, v32, v33 offset0:108 offset1:140
	s_waitcnt lgkmcnt(0)
	s_barrier
	ds_read_b128 v[32:35], v208
	v_lshl_add_u64 v[36:37], s[46:47], 0, v[188:189]
	v_lshl_add_u64 v[36:37], v[36:37], 0, s[30:31]
	v_lshl_add_u64 v[36:37], v[36:37], 0, v[116:117]
	v_or_b32_e32 v40, s20, v100
	v_lshlrev_b32_e32 v40, 8, v40
	v_and_b32_e32 v60, 0x3e000, v40
	v_mov_b32_e32 v61, v117
	s_waitcnt vmcnt(7) lgkmcnt(0)
	v_pk_add_f32 v[34:35], v[94:95], v[34:35]
	v_pk_add_f32 v[32:33], v[92:93], v[32:33]
	global_store_dwordx4 v[36:37], v[32:35], off
	v_pk_mul_f32 v[38:39], v[152:153], v[32:33]
	v_pk_mul_f32 v[36:37], v[154:155], v[34:35]
	v_mul_f32_e32 v33, v33, v33
	v_fmac_f32_e32 v33, v32, v32
	v_and_b32_e32 v32, 64, v213
	v_fmac_f32_e32 v33, v34, v34
	v_add_u32_e32 v34, 64, v32
	v_xor_b32_e32 v32, 16, v213
	v_cmp_lt_i32_e64 s[0:1], v32, v34
	v_fmac_f32_e32 v33, v35, v35
	v_cvt_pk_bf16_f32 v38, v38, v39
	v_cndmask_b32_e64 v32, v213, v32, s[0:1]
	v_lshlrev_b32_e32 v92, 2, v32
	ds_bpermute_b32 v32, v92, v33
	v_cvt_pk_bf16_f32 v39, v36, v37
	v_ashrrev_i32_e32 v36, 7, v186
	v_ashrrev_i32_e32 v37, 31, v36
	v_lshlrev_b64 v[36:37], 18, v[36:37]
	s_waitcnt lgkmcnt(0)
	v_add_f32_e32 v32, v33, v32
	v_xor_b32_e32 v33, 8, v213
	v_cmp_lt_i32_e64 s[0:1], v33, v34
	v_lshl_add_u64 v[36:37], s[10:11], 0, v[36:37]
	v_lshl_add_u64 v[36:37], v[36:37], 0, v[60:61]
	v_cndmask_b32_e64 v33, v213, v33, s[0:1]
	v_lshlrev_b32_e32 v93, 2, v33
	ds_bpermute_b32 v33, v93, v32
	v_lshl_add_u64 v[36:37], v[36:37], 0, v[106:107]
	v_lshl_add_u64 v[36:37], v[36:37], 0, v[108:109]
	global_store_dwordx2 v[36:37], v[38:39], off
	s_waitcnt lgkmcnt(0)
	v_add_f32_e32 v32, v32, v33
	v_xor_b32_e32 v33, 4, v213
	v_cmp_lt_i32_e64 s[0:1], v33, v34
	s_nop 1
	v_cndmask_b32_e64 v33, v213, v33, s[0:1]
	v_lshlrev_b32_e32 v94, 2, v33
	ds_bpermute_b32 v33, v94, v32
	s_waitcnt lgkmcnt(0)
	v_add_f32_e32 v32, v32, v33
	v_xor_b32_e32 v33, 2, v213
	v_cmp_lt_i32_e64 s[0:1], v33, v34
	s_nop 1
	v_cndmask_b32_e64 v33, v213, v33, s[0:1]
	v_lshlrev_b32_e32 v95, 2, v33
	ds_bpermute_b32 v33, v95, v32
	s_waitcnt lgkmcnt(0)
	v_add_f32_e32 v32, v32, v33
	v_xor_b32_e32 v33, 1, v213
	v_cmp_lt_i32_e64 s[0:1], v33, v34
	s_nop 1
	v_cndmask_b32_e64 v33, v213, v33, s[0:1]
	v_lshlrev_b32_e32 v107, 2, v33
	ds_bpermute_b32 v33, v107, v32
	s_and_saveexec_b64 s[0:1], vcc
	s_cbranch_execz .LBB0_150
	s_waitcnt lgkmcnt(0)
	v_add_f32_e32 v32, v32, v33
	v_fma_f32 v32, v32, s75, 0.5
	v_cvt_u32_f32_e32 v34, v32
	v_lshl_add_u64 v[32:33], v[186:187], 2, s[8:9]
	global_atomic_add v[32:33], v34, off

.LBB0_164:
	s_or_b64 exec, exec, s[0:1]
	v_add_u32_e32 v90, s21, v200
	v_ashrrev_i32_e32 v91, 31, v90
	v_add_u32_e32 v86, s21, v201
	v_lshlrev_b64 v[162:163], 12, v[90:91]
	v_ashrrev_i32_e32 v87, 31, v86
	s_waitcnt lgkmcnt(0)
	v_lshl_add_u64 v[32:33], v[156:157], 0, v[162:163]
	v_lshlrev_b64 v[88:89], 12, v[86:87]
	s_waitcnt lgkmcnt(0)
	s_barrier
	v_lshl_add_u64 v[34:35], v[156:157], 0, v[88:89]
	global_load_dwordx4 v[158:161], v[32:33], off sc1
	global_load_dwordx4 v[56:59], v[34:35], off sc1
	v_add_u32_e32 v82, s21, v202
	v_add_u32_e32 v78, s21, v203
	v_ashrrev_i32_e32 v83, 31, v82
	v_ashrrev_i32_e32 v79, 31, v78
	v_add_u32_e32 v74, s21, v204
	v_add_u32_e32 v70, s21, v205
	v_lshlrev_b64 v[84:85], 12, v[82:83]
	v_lshlrev_b64 v[80:81], 12, v[78:79]
	v_ashrrev_i32_e32 v75, 31, v74
	v_ashrrev_i32_e32 v71, 31, v70
	v_add_u32_e32 v66, s21, v206
	v_add_u32_e32 v62, s21, v207
	v_lshl_add_u64 v[32:33], v[156:157], 0, v[84:85]
	v_lshl_add_u64 v[34:35], v[156:157], 0, v[80:81]
	v_lshlrev_b64 v[76:77], 12, v[74:75]
	v_lshlrev_b64 v[72:73], 12, v[70:71]
	v_ashrrev_i32_e32 v67, 31, v66
	v_ashrrev_i32_e32 v63, 31, v62
	global_load_dwordx4 v[52:55], v[32:33], off sc1
	global_load_dwordx4 v[48:51], v[34:35], off sc1
	v_lshl_add_u64 v[32:33], v[156:157], 0, v[76:77]
	v_lshl_add_u64 v[34:35], v[156:157], 0, v[72:73]
	v_lshlrev_b64 v[68:69], 12, v[66:67]
	v_lshlrev_b64 v[64:65], 12, v[62:63]
	global_load_dwordx4 v[44:47], v[32:33], off sc1
	global_load_dwordx4 v[40:43], v[34:35], off sc1
	v_lshl_add_u64 v[32:33], v[156:157], 0, v[68:69]
	v_lshl_add_u64 v[34:35], v[156:157], 0, v[64:65]
	global_load_dwordx4 v[36:39], v[32:33], off sc1
	s_nop 0
	global_load_dwordx4 v[32:35], v[34:35], off sc1
	v_mul_f32_e32 v0, v0, v137
	v_mul_f32_e32 v16, v16, v139
	ds_write2_b32 v199, v0, v16 offset1:32
	v_mul_f32_e32 v0, v1, v137
	v_mul_f32_e32 v1, v17, v139
	ds_write2_b32 v199, v0, v1 offset0:132 offset1:164
	v_mul_f32_e32 v0, v2, v137
	v_mul_f32_e32 v1, v18, v139
	ds_write2_b32 v141, v0, v1 offset0:8 offset1:40
	v_mul_f32_e32 v0, v3, v137
	v_mul_f32_e32 v1, v19, v139
	ds_write2_b32 v141, v0, v1 offset0:140 offset1:172
	v_mul_f32_e32 v0, v4, v137
	v_mul_f32_e32 v1, v20, v139
	ds_write2_b32 v143, v0, v1 offset0:32 offset1:64
	v_mul_f32_e32 v0, v5, v137
	v_mul_f32_e32 v1, v21, v139
	ds_write2_b32 v143, v0, v1 offset0:164 offset1:196
	v_mul_f32_e32 v0, v6, v137
	v_mul_f32_e32 v1, v22, v139
	ds_write2_b32 v145, v0, v1 offset0:40 offset1:72
	v_mul_f32_e32 v0, v7, v137
	v_mul_f32_e32 v1, v23, v139
	ds_write2_b32 v145, v0, v1 offset0:172 offset1:204
	v_mul_f32_e32 v0, v8, v137
	v_mul_f32_e32 v1, v24, v139
	ds_write2_b32 v147, v0, v1 offset0:64 offset1:96
	v_mul_f32_e32 v0, v9, v137
	v_mul_f32_e32 v1, v25, v139
	ds_write2_b32 v147, v0, v1 offset0:196 offset1:228
	v_mul_f32_e32 v0, v10, v137
	v_mul_f32_e32 v1, v26, v139
	ds_write2_b32 v149, v0, v1 offset0:72 offset1:104
	v_mul_f32_e32 v0, v11, v137
	v_mul_f32_e32 v1, v27, v139
	ds_write2_b32 v149, v0, v1 offset0:204 offset1:236
	v_mul_f32_e32 v0, v12, v137
	v_mul_f32_e32 v1, v28, v139
	ds_write2_b32 v151, v0, v1 offset0:96 offset1:128
	v_mul_f32_e32 v0, v13, v137
	v_mul_f32_e32 v1, v29, v139
	ds_write2_b32 v209, v0, v1 offset0:100 offset1:132
	v_mul_f32_e32 v0, v14, v137
	v_mul_f32_e32 v1, v30, v139
	ds_write2_b32 v210, v0, v1 offset0:104 offset1:136
	v_mul_f32_e32 v0, v15, v137
	v_mul_f32_e32 v1, v31, v139
	ds_write2_b32 v211, v0, v1 offset0:108 offset1:140
	s_waitcnt lgkmcnt(0)
	s_barrier
	ds_read_b128 v[0:3], v208
	v_lshl_add_u64 v[4:5], s[46:47], 0, v[162:163]
	v_lshl_add_u64 v[4:5], v[4:5], 0, s[30:31]
	v_lshl_add_u64 v[4:5], v[4:5], 0, v[116:117]
	v_mov_b32_e32 v137, v117
	s_waitcnt vmcnt(7) lgkmcnt(0)
	v_pk_add_f32 v[0:1], v[158:159], v[0:1]
	v_pk_add_f32 v[2:3], v[160:161], v[2:3]
	v_mul_f32_e32 v6, v1, v1
	v_fmac_f32_e32 v6, v0, v0
	v_fmac_f32_e32 v6, v2, v2
	v_fmac_f32_e32 v6, v3, v3
	ds_bpermute_b32 v7, v92, v6
	global_store_dwordx4 v[4:5], v[0:3], off
	v_mov_b32_e32 v109, v117
	s_waitcnt lgkmcnt(0)
	v_add_f32_e32 v6, v6, v7
	ds_bpermute_b32 v7, v93, v6
	v_pk_mul_f32 v[0:1], v[152:153], v[0:1]
	v_pk_mul_f32 v[2:3], v[154:155], v[2:3]
	v_cvt_pk_bf16_f32 v4, v0, v1
	v_ashrrev_i32_e32 v0, 7, v90
	s_waitcnt lgkmcnt(0)
	v_add_f32_e32 v6, v6, v7
	ds_bpermute_b32 v7, v94, v6
	v_ashrrev_i32_e32 v1, 31, v0
	v_lshlrev_b64 v[0:1], 18, v[0:1]
	v_lshl_add_u64 v[0:1], s[10:11], 0, v[0:1]
	v_cvt_pk_bf16_f32 v5, v2, v3
	s_waitcnt lgkmcnt(0)
	v_add_f32_e32 v6, v6, v7
	ds_bpermute_b32 v7, v95, v6
	v_lshl_add_u64 v[2:3], v[0:1], 0, v[60:61]
	v_lshl_add_u64 v[2:3], v[2:3], 0, v[136:137]
	v_lshl_add_u64 v[2:3], v[2:3], 0, v[108:109]
	global_store_dwordx2 v[2:3], v[4:5], off
	s_waitcnt lgkmcnt(0)
	v_add_f32_e32 v0, v6, v7
	ds_bpermute_b32 v1, v107, v0
	s_and_saveexec_b64 s[0:1], vcc
	s_cbranch_execz .LBB0_166
	s_waitcnt lgkmcnt(0)
	v_add_f32_e32 v0, v0, v1
	v_fma_f32 v0, v0, s75, 0.5
	v_cvt_u32_f32_e32 v2, v0
	v_lshl_add_u64 v[0:1], v[90:91], 2, s[8:9]
	global_atomic_add v[0:1], v2, off

.LBB0_188:
	s_lshl_b32 s8, s20, 12
	s_and_b32 s30, s8, 0x380000
	s_and_b32 s8, s18, -8
	s_or_b32 s8, s19, s8
	s_ashr_i32 s9, s8, 31
	s_lshl_b64 s[10:11], s[8:9], 19
	v_lshl_add_u64 v[206:207], v[104:105], 0, s[10:11]
	s_lshl_b32 s9, s18, 7
	v_lshl_add_u64 v[0:1], v[96:97], 0, s[10:11]
	v_readfirstlane_b32 s11, v119
	v_add_u32_e32 v107, 0x400, v119
	s_and_b32 s9, s9, 0x380
	s_mov_b32 m0, s11
	s_mov_b64 s[14:15], 0x400
	v_readfirstlane_b32 s11, v107
	v_add_u32_e32 v109, 0x2000, v119
	v_lshl_add_u64 v[204:205], v[102:103], 0, s[30:31]
	s_lshl_b32 s30, s9, 12
	global_load_lds_dwordx4 v[0:1], off sc1
	v_lshl_add_u64 v[4:5], v[0:1], 0, s[14:15]
	s_mov_b32 m0, s11
	v_readfirstlane_b32 s11, v109
	v_add_u32_e32 v111, 0x2400, v119
	v_lshl_add_u64 v[2:3], v[98:99], 0, s[30:31]
	global_load_lds_dwordx4 v[4:5], off sc1
	s_mov_b32 m0, s11
	v_readfirstlane_b32 s11, v111
	v_add_u32_e32 v113, 0x4000, v119
	global_load_lds_dwordx4 v[2:3], off sc1
	v_lshl_add_u64 v[4:5], v[2:3], 0, s[14:15]
	s_mov_b32 m0, s11
	v_readfirstlane_b32 s11, v113
	v_add_u32_e32 v115, 0x4400, v119
	global_load_lds_dwordx4 v[4:5], off sc1
	v_lshl_add_u64 v[4:5], v[0:1], 0, s[44:45]
	s_mov_b32 m0, s11
	v_readfirstlane_b32 s11, v115
	v_add_u32_e32 v129, 0x6000, v119
	global_load_lds_dwordx4 v[4:5], off sc1
	v_lshl_add_u64 v[4:5], v[0:1], 0, s[66:67]
	s_mov_b32 m0, s11
	v_readfirstlane_b32 s11, v129
	v_add_u32_e32 v131, 0x6400, v119
	global_load_lds_dwordx4 v[4:5], off sc1
	v_lshl_add_u64 v[4:5], v[2:3], 0, s[44:45]
	s_mov_b32 m0, s11
	v_readfirstlane_b32 s11, v131
	v_add_u32_e32 v133, 0x8000, v119
	global_load_lds_dwordx4 v[4:5], off sc1
	v_lshl_add_u64 v[4:5], v[2:3], 0, s[66:67]
	s_mov_b32 m0, s11
	v_readfirstlane_b32 s11, v133
	v_add_u32_e32 v135, 0x8400, v119
	global_load_lds_dwordx4 v[4:5], off sc1
	v_lshl_add_u64 v[4:5], v[0:1], 0, s[28:29]
	s_mov_b32 m0, s11
	s_mov_b64 s[14:15], 0x4400
	v_readfirstlane_b32 s11, v135
	v_add_u32_e32 v137, 0xa000, v119
	global_load_lds_dwordx4 v[4:5], off sc1
	v_lshl_add_u64 v[0:1], v[0:1], 0, s[14:15]
	s_mov_b32 m0, s11
	v_readfirstlane_b32 s11, v137
	v_add_u32_e32 v139, 0xa400, v119
	global_load_lds_dwordx4 v[0:1], off sc1
	v_lshl_add_u64 v[0:1], v[2:3], 0, s[28:29]
	s_mov_b32 m0, s11
	v_readfirstlane_b32 s11, v139
	global_load_lds_dwordx4 v[0:1], off sc1
	v_lshl_add_u64 v[0:1], v[2:3], 0, s[14:15]
	s_mov_b32 m0, s11
	s_and_b32 s10, s18, 7
	global_load_lds_dwordx4 v[0:1], off sc1
	s_lshl_b32 s11, s8, 5
	v_mov_b32_e32 v0, 0
	s_or_b32 s22, s11, s10
	s_mov_b64 s[10:11], 0
	s_mov_b32 s23, 0
	s_mov_b32 s30, 0
	v_mov_b32_e32 v1, v0
	v_mov_b32_e32 v2, v0
	v_mov_b32_e32 v3, v0
	v_mov_b32_e32 v4, v0
	v_mov_b32_e32 v5, v0
	v_mov_b32_e32 v6, v0
	v_mov_b32_e32 v7, v0
	v_mov_b32_e32 v8, v0
	v_mov_b32_e32 v9, v0
	v_mov_b32_e32 v10, v0
	v_mov_b32_e32 v11, v0
	v_mov_b32_e32 v12, v0
	v_mov_b32_e32 v13, v0
	v_mov_b32_e32 v14, v0
	v_mov_b32_e32 v15, v0
	v_mov_b32_e32 v16, v0
	v_mov_b32_e32 v17, v0
	v_mov_b32_e32 v18, v0
	v_mov_b32_e32 v19, v0
	v_mov_b32_e32 v20, v0
	v_mov_b32_e32 v21, v0
	v_mov_b32_e32 v22, v0
	v_mov_b32_e32 v23, v0
	v_mov_b32_e32 v24, v0
	v_mov_b32_e32 v25, v0
	v_mov_b32_e32 v26, v0
	v_mov_b32_e32 v27, v0
	v_mov_b32_e32 v28, v0
	v_mov_b32_e32 v29, v0
	v_mov_b32_e32 v30, v0
	v_mov_b32_e32 v31, v0
	s_waitcnt vmcnt(0)
	v_mov_b32_e32 v32, v0
	v_mov_b32_e32 v33, v0
	v_mov_b32_e32 v34, v0
	v_mov_b32_e32 v35, v0
	v_mov_b32_e32 v36, v0
	v_mov_b32_e32 v37, v0
	v_mov_b32_e32 v38, v0
	v_mov_b32_e32 v39, v0
	v_mov_b32_e32 v40, v0
	v_mov_b32_e32 v41, v0
	v_mov_b32_e32 v42, v0
	v_mov_b32_e32 v43, v0
	v_mov_b32_e32 v44, v0
	v_mov_b32_e32 v45, v0
	v_mov_b32_e32 v46, v0
	v_mov_b32_e32 v47, v0
	v_mov_b32_e32 v48, v0
	v_mov_b32_e32 v49, v0
	v_mov_b32_e32 v50, v0
	v_mov_b32_e32 v51, v0
	v_mov_b32_e32 v52, v0
	v_mov_b32_e32 v53, v0
	v_mov_b32_e32 v54, v0
	v_mov_b32_e32 v55, v0
	v_mov_b32_e32 v56, v0
	v_mov_b32_e32 v57, v0
	v_mov_b32_e32 v58, v0
	v_mov_b32_e32 v59, v0
	v_mov_b32_e32 v60, v0
	v_mov_b32_e32 v61, v0
	v_mov_b32_e32 v62, v0
	v_mov_b32_e32 v63, v0
	v_mov_b32_e32 v162, v0
	v_mov_b32_e32 v163, v0
	v_mov_b32_e32 v158, v0
	v_mov_b32_e32 v159, v0
	v_mov_b32_e32 v154, v0
	v_mov_b32_e32 v155, v0
	v_mov_b32_e32 v150, v0
	v_mov_b32_e32 v151, v0
	v_mov_b32_e32 v146, v0
	v_mov_b32_e32 v147, v0
	v_mov_b32_e32 v144, v0
	v_mov_b32_e32 v145, v0
	v_mov_b32_e32 v142, v0
	v_mov_b32_e32 v143, v0
	v_mov_b32_e32 v140, v0
	v_mov_b32_e32 v141, v0
	v_mov_b32_e32 v170, v0
	v_mov_b32_e32 v171, v0
	v_mov_b32_e32 v168, v0
	v_mov_b32_e32 v169, v0
	v_mov_b32_e32 v166, v0
	v_mov_b32_e32 v167, v0
	v_mov_b32_e32 v164, v0
	v_mov_b32_e32 v165, v0
	v_mov_b32_e32 v160, v0
	v_mov_b32_e32 v161, v0
	v_mov_b32_e32 v156, v0
	v_mov_b32_e32 v157, v0
	v_mov_b32_e32 v152, v0
	v_mov_b32_e32 v153, v0
	v_mov_b32_e32 v148, v0
	v_mov_b32_e32 v149, v0
	v_mov_b32_e32 v194, v0
	v_mov_b32_e32 v195, v0
	v_mov_b32_e32 v190, v0
	v_mov_b32_e32 v191, v0
	v_mov_b32_e32 v186, v0
	v_mov_b32_e32 v187, v0
	v_mov_b32_e32 v182, v0
	v_mov_b32_e32 v183, v0
	v_mov_b32_e32 v178, v0
	v_mov_b32_e32 v179, v0
	v_mov_b32_e32 v176, v0
	v_mov_b32_e32 v177, v0
	v_mov_b32_e32 v174, v0
	v_mov_b32_e32 v175, v0
	v_mov_b32_e32 v172, v0
	v_mov_b32_e32 v173, v0
	v_mov_b32_e32 v202, v0
	v_mov_b32_e32 v203, v0
	v_mov_b32_e32 v200, v0
	v_mov_b32_e32 v201, v0
	v_mov_b32_e32 v198, v0
	v_mov_b32_e32 v199, v0
	v_mov_b32_e32 v196, v0
	v_mov_b32_e32 v197, v0
	v_mov_b32_e32 v192, v0
	v_mov_b32_e32 v193, v0
	v_mov_b32_e32 v188, v0
	v_mov_b32_e32 v189, v0
	v_mov_b32_e32 v184, v0
	v_mov_b32_e32 v185, v0
	v_mov_b32_e32 v180, v0
	v_mov_b32_e32 v181, v0
	s_branch .LBB0_190

.LBB0_190:
	s_waitcnt vmcnt(8)
	v_add_u32_e32 v245, v227, v122
	v_add_u32_e32 v246, v125, v122
	v_add_u32_e32 v247, v227, v121
	v_add_u32_e32 v248, v125, v121
	s_waitcnt lgkmcnt(0)
	s_barrier
	ds_read_b128 v[64:67], v245
	ds_read_b128 v[68:71], v245 offset:2048
	ds_read_b128 v[72:75], v246 offset:8192
	ds_read_b128 v[76:79], v246 offset:10240
	ds_read_b128 v[80:83], v247
	ds_read_b128 v[84:87], v247 offset:2048
	ds_read_b128 v[88:91], v248 offset:8192
	ds_read_b128 v[92:95], v248 offset:10240
	v_lshl_add_u64 v[208:209], v[204:205], 0, s[10:11]
	s_mov_b64 s[14:15], 0x3c54000
	v_lshl_add_u64 v[250:251], v[208:209], 0, s[14:15]
	s_mov_b64 s[14:15], 0x3c54400
	v_lshl_add_u64 v[252:253], v[208:209], 0, s[14:15]
	v_lshl_add_u64 v[210:211], v[206:207], 0, s[10:11]
	s_mov_b64 s[14:15], 0x148d4000
	v_lshl_add_u64 v[216:217], v[210:211], 0, s[14:15]
	s_mov_b64 s[14:15], 0x148d4400
	v_add_u32_e32 v226, 0xc000, v119
	v_lshl_add_u64 v[214:215], v[210:211], 0, s[14:15]
	v_readfirstlane_b32 s14, v226
	s_mov_b32 m0, s14
	s_nop 0
	global_load_lds_dwordx4 v[216:217], off sc1
	v_add_u32_e32 v216, 0xc400, v119
	s_nop 0
	v_readfirstlane_b32 s14, v216
	s_mov_b32 m0, s14
	s_nop 0
	global_load_lds_dwordx4 v[214:215], off sc1
	v_add_u32_e32 v214, 0xe000, v119
	s_nop 0
	v_readfirstlane_b32 s14, v214
	v_add_u32_e32 v214, 0xe400, v119
	s_mov_b32 m0, s14
	v_readfirstlane_b32 s14, v214
	global_load_lds_dwordx4 v[250:251], off sc1
	s_mov_b32 m0, s14
	s_nop 0
	global_load_lds_dwordx4 v[252:253], off sc1
	s_waitcnt lgkmcnt(0)
	v_mfma_f32_32x32x16_bf16 v[48:63], v[64:67], v[72:75], v[48:63]
	s_waitcnt vmcnt(8)
	s_waitcnt lgkmcnt(0)
	s_barrier
	v_mfma_f32_32x32x16_bf16 v[32:47], v[64:67], v[76:79], v[32:47]
	v_mfma_f32_32x32x16_bf16 v[16:31], v[68:71], v[72:75], v[16:31]
	v_mfma_f32_32x32x16_bf16 v[0:15], v[68:71], v[76:79], v[0:15]
	v_mfma_f32_32x32x16_bf16 v[48:63], v[80:83], v[88:91], v[48:63]
	v_mfma_f32_32x32x16_bf16 v[32:47], v[80:83], v[92:95], v[32:47]
	v_mfma_f32_32x32x16_bf16 v[16:31], v[84:87], v[88:91], v[16:31]
	v_mfma_f32_32x32x16_bf16 v[0:15], v[84:87], v[92:95], v[0:15]
	ds_read_b128 v[88:91], v245 offset:16384
	ds_read_b128 v[80:83], v245 offset:18432
	ds_read_b128 v[92:95], v246 offset:24576
	ds_read_b128 v[84:87], v246 offset:26624
	ds_read_b128 v[72:75], v247 offset:16384
	ds_read_b128 v[64:67], v247 offset:18432
	ds_read_b128 v[76:79], v248 offset:24576
	ds_read_b128 v[68:71], v248 offset:26624
	s_cmp_gt_u32 s30, 59
	s_cselect_b64 s[14:15], -1, 0
	s_cmp_lt_u32 s30, 60
	s_cbranch_scc0 .LBB0_192
	s_mov_b64 s[16:17], 0x3c56000
	v_lshl_add_u64 v[214:215], v[208:209], 0, s[16:17]
	s_mov_b64 s[16:17], 0x3c56400
	v_lshl_add_u64 v[216:217], v[208:209], 0, s[16:17]
	s_mov_b64 s[16:17], 0x148d6000
	v_lshl_add_u64 v[250:251], v[210:211], 0, s[16:17]
	s_mov_b64 s[16:17], 0x148d6400
	v_lshl_add_u64 v[252:253], v[210:211], 0, s[16:17]
	v_readfirstlane_b32 s16, v119
	s_mov_b32 m0, s16
	v_readfirstlane_b32 s16, v107
	global_load_lds_dwordx4 v[250:251], off sc1
	s_mov_b32 m0, s16
	v_readfirstlane_b32 s16, v109
	global_load_lds_dwordx4 v[252:253], off sc1
	s_mov_b32 m0, s16
	v_readfirstlane_b32 s16, v111
	global_load_lds_dwordx4 v[214:215], off sc1
	s_mov_b32 m0, s16
	s_nop 0
	global_load_lds_dwordx4 v[216:217], off sc1

.LBB0_200:
	s_waitcnt lgkmcnt(0)
	s_barrier
	ds_read_b128 v[88:91], v245 offset:32768
	ds_read_b128 v[80:83], v245 offset:34816
	ds_read_b128 v[92:95], v246 offset:40960
	ds_read_b128 v[84:87], v246 offset:43008
	ds_read_b128 v[72:75], v247 offset:32768
	ds_read_b128 v[64:67], v247 offset:34816
	ds_read_b128 v[76:79], v248 offset:40960
	ds_read_b128 v[68:71], v248 offset:43008
	s_cmp_gt_u32 s30, 58
	s_cbranch_scc1 .LBB0_202
	s_mov_b64 s[16:17], 0x3c58000
	v_lshl_add_u64 v[214:215], v[208:209], 0, s[16:17]
	s_mov_b64 s[16:17], 0x3c58400
	v_lshl_add_u64 v[216:217], v[208:209], 0, s[16:17]
	s_mov_b64 s[16:17], 0x148d8000
	v_lshl_add_u64 v[250:251], v[210:211], 0, s[16:17]
	s_mov_b64 s[16:17], 0x148d8400
	v_lshl_add_u64 v[252:253], v[210:211], 0, s[16:17]
	v_readfirstlane_b32 s16, v113
	s_mov_b32 m0, s16
	v_readfirstlane_b32 s16, v115
	global_load_lds_dwordx4 v[250:251], off sc1
	s_mov_b32 m0, s16
	v_readfirstlane_b32 s16, v129
	global_load_lds_dwordx4 v[252:253], off sc1
	s_mov_b32 m0, s16
	v_readfirstlane_b32 s16, v131
	global_load_lds_dwordx4 v[214:215], off sc1
	s_mov_b32 m0, s16
	s_nop 0
	global_load_lds_dwordx4 v[216:217], off sc1

.LBB0_206:
	s_waitcnt lgkmcnt(0)
	s_barrier
	ds_read_b128 v[88:91], v245 offset:49152
	ds_read_b128 v[80:83], v245 offset:51200
	ds_read_b128 v[92:95], v246 offset:57344
	ds_read_b128 v[84:87], v246 offset:59392
	ds_read_b128 v[72:75], v247 offset:49152
	ds_read_b128 v[64:67], v247 offset:51200
	ds_read_b128 v[76:79], v248 offset:57344
	ds_read_b128 v[68:71], v248 offset:59392
	s_cmp_gt_u32 s30, 57
	s_cbranch_scc1 .LBB0_208
	s_mov_b64 s[16:17], 0x3c5a000
	v_lshl_add_u64 v[214:215], v[208:209], 0, s[16:17]
	s_mov_b64 s[16:17], 0x3c5a400
	v_lshl_add_u64 v[208:209], v[208:209], 0, s[16:17]
	s_mov_b64 s[16:17], 0x148da000
	v_lshl_add_u64 v[216:217], v[210:211], 0, s[16:17]
	s_mov_b64 s[16:17], 0x148da400
	v_lshl_add_u64 v[210:211], v[210:211], 0, s[16:17]
	v_readfirstlane_b32 s16, v133
	s_mov_b32 m0, s16
	v_readfirstlane_b32 s16, v135
	global_load_lds_dwordx4 v[216:217], off sc1
	s_mov_b32 m0, s16
	v_readfirstlane_b32 s16, v137
	global_load_lds_dwordx4 v[210:211], off sc1
	s_mov_b32 m0, s16
	v_readfirstlane_b32 s16, v139
	global_load_lds_dwordx4 v[214:215], off sc1
	s_mov_b32 m0, s16
	s_nop 0
	global_load_lds_dwordx4 v[208:209], off sc1
.LBB0_208:
	s_waitcnt lgkmcnt(0)
	v_mfma_f32_32x32x16_bf16 v[48:63], v[88:91], v[92:95], v[48:63]
	s_and_b32 s16, s30, 12
	s_cmp_lg_u32 s16, 12
	v_mfma_f32_32x32x16_bf16 v[32:47], v[88:91], v[84:87], v[32:47]
	v_mfma_f32_32x32x16_bf16 v[16:31], v[80:83], v[92:95], v[16:31]
	v_mfma_f32_32x32x16_bf16 v[0:15], v[80:83], v[84:87], v[0:15]
	v_mfma_f32_32x32x16_bf16 v[48:63], v[72:75], v[76:79], v[48:63]
	v_mfma_f32_32x32x16_bf16 v[32:47], v[72:75], v[68:71], v[32:47]
	v_mfma_f32_32x32x16_bf16 v[16:31], v[64:67], v[76:79], v[16:31]
	v_mfma_f32_32x32x16_bf16 v[0:15], v[64:67], v[68:71], v[0:15]
	s_cbranch_scc1 .LBB0_189
	s_and_b32 s16, s23, 0x3ffffff8
	s_add_i32 s16, s22, s16
	s_ashr_i32 s17, s16, 31
	s_lshl_b64 s[16:17], s[16:17], 15
	v_lshl_add_u64 v[64:65], v[100:101], 0, s[16:17]
	global_load_dwordx4 v[66:69], v[64:65], off sc1 nt
	v_add_co_u32_e32 v214, vcc, 0x1000, v64
	s_nop 1
	v_addc_co_u32_e32 v215, vcc, 0, v65, vcc
	global_load_dwordx4 v[70:73], v[214:215], off sc1 nt
	v_add_co_u32_e32 v216, vcc, s79, v64
	s_nop 1
	v_addc_co_u32_e32 v217, vcc, 0, v65, vcc
	global_load_dwordx4 v[74:77], v[216:217], off offset:-4096 sc1 nt
	global_load_dwordx4 v[78:81], v[216:217], off sc1 nt
	v_add_co_u32_e32 v214, vcc, s76, v64
	s_nop 1
	v_addc_co_u32_e32 v215, vcc, 0, v65, vcc
	global_load_dwordx4 v[82:85], v[214:215], off offset:-4096 sc1 nt
	global_load_dwordx4 v[86:89], v[214:215], off sc1 nt
	v_add_co_u32_e32 v216, vcc, s78, v64
	s_nop 1
	v_addc_co_u32_e32 v217, vcc, 0, v65, vcc
	global_load_dwordx4 v[90:93], v[216:217], off offset:-4096 sc1 nt
	global_load_dwordx4 v[250:253], v[216:217], off sc1 nt
	s_waitcnt vmcnt(7)
	v_lshlrev_b32_e32 v94, 16, v66
	v_and_b32_e32 v95, 0xffff0000, v66
	v_pk_fma_f32 v[202:203], v[48:49], v[94:95], v[202:203]
	v_lshlrev_b32_e32 v214, 16, v67
	v_and_b32_e32 v215, 0xffff0000, v67
	v_pk_fma_f32 v[200:201], v[50:51], v[214:215], v[200:201]
	v_lshlrev_b32_e32 v94, 16, v68
	v_and_b32_e32 v95, 0xffff0000, v68
	v_pk_fma_f32 v[198:199], v[52:53], v[94:95], v[198:199]
	v_lshlrev_b32_e32 v214, 16, v69
	v_and_b32_e32 v215, 0xffff0000, v69
	v_pk_fma_f32 v[196:197], v[54:55], v[214:215], v[196:197]
	s_waitcnt vmcnt(6)
	v_lshlrev_b32_e32 v94, 16, v70
	v_and_b32_e32 v95, 0xffff0000, v70
	v_pk_fma_f32 v[192:193], v[56:57], v[94:95], v[192:193]
	v_lshlrev_b32_e32 v214, 16, v71
	v_and_b32_e32 v215, 0xffff0000, v71
	v_pk_fma_f32 v[188:189], v[58:59], v[214:215], v[188:189]
	v_lshlrev_b32_e32 v94, 16, v72
	v_and_b32_e32 v95, 0xffff0000, v72
	v_pk_fma_f32 v[184:185], v[60:61], v[94:95], v[184:185]
	v_lshlrev_b32_e32 v214, 16, v73
	v_and_b32_e32 v215, 0xffff0000, v73
	v_pk_fma_f32 v[180:181], v[62:63], v[214:215], v[180:181]
	s_waitcnt vmcnt(5)
	v_lshlrev_b32_e32 v94, 16, v74
	v_and_b32_e32 v95, 0xffff0000, v74
	v_pk_fma_f32 v[194:195], v[32:33], v[94:95], v[194:195]
	v_lshlrev_b32_e32 v214, 16, v75
	v_and_b32_e32 v215, 0xffff0000, v75
	v_pk_fma_f32 v[190:191], v[34:35], v[214:215], v[190:191]
	v_lshlrev_b32_e32 v94, 16, v76
	v_and_b32_e32 v95, 0xffff0000, v76
	v_pk_fma_f32 v[186:187], v[36:37], v[94:95], v[186:187]
	v_lshlrev_b32_e32 v214, 16, v77
	v_and_b32_e32 v215, 0xffff0000, v77
	v_pk_fma_f32 v[182:183], v[38:39], v[214:215], v[182:183]
	s_waitcnt vmcnt(4)
	v_lshlrev_b32_e32 v94, 16, v78
	v_and_b32_e32 v95, 0xffff0000, v78
	v_pk_fma_f32 v[178:179], v[40:41], v[94:95], v[178:179]
	v_lshlrev_b32_e32 v214, 16, v79
	v_and_b32_e32 v215, 0xffff0000, v79
	v_pk_fma_f32 v[176:177], v[42:43], v[214:215], v[176:177]
	v_lshlrev_b32_e32 v94, 16, v80
	v_and_b32_e32 v95, 0xffff0000, v80
	v_pk_fma_f32 v[174:175], v[44:45], v[94:95], v[174:175]
	v_lshlrev_b32_e32 v214, 16, v81
	v_and_b32_e32 v215, 0xffff0000, v81
	v_pk_fma_f32 v[172:173], v[46:47], v[214:215], v[172:173]
	s_waitcnt vmcnt(3)
	v_lshlrev_b32_e32 v94, 16, v82
	v_and_b32_e32 v95, 0xffff0000, v82
	v_pk_fma_f32 v[170:171], v[16:17], v[94:95], v[170:171]
	v_lshlrev_b32_e32 v214, 16, v83
	v_and_b32_e32 v215, 0xffff0000, v83
	v_pk_fma_f32 v[168:169], v[18:19], v[214:215], v[168:169]
	v_lshlrev_b32_e32 v94, 16, v84
	v_and_b32_e32 v95, 0xffff0000, v84
	v_pk_fma_f32 v[166:167], v[20:21], v[94:95], v[166:167]
	v_lshlrev_b32_e32 v214, 16, v85
	v_and_b32_e32 v215, 0xffff0000, v85
	v_pk_fma_f32 v[164:165], v[22:23], v[214:215], v[164:165]
	s_waitcnt vmcnt(2)
	v_lshlrev_b32_e32 v94, 16, v86
	v_and_b32_e32 v95, 0xffff0000, v86
	v_pk_fma_f32 v[160:161], v[24:25], v[94:95], v[160:161]
	v_lshlrev_b32_e32 v214, 16, v87
	v_and_b32_e32 v215, 0xffff0000, v87
	v_pk_fma_f32 v[156:157], v[26:27], v[214:215], v[156:157]
	v_lshlrev_b32_e32 v94, 16, v88
	v_and_b32_e32 v95, 0xffff0000, v88
	v_pk_fma_f32 v[152:153], v[28:29], v[94:95], v[152:153]
	v_lshlrev_b32_e32 v214, 16, v89
	v_and_b32_e32 v215, 0xffff0000, v89
	v_pk_fma_f32 v[148:149], v[30:31], v[214:215], v[148:149]
	s_waitcnt vmcnt(1)
	v_lshlrev_b32_e32 v94, 16, v90
	v_and_b32_e32 v95, 0xffff0000, v90
	v_pk_fma_f32 v[162:163], v[0:1], v[94:95], v[162:163]
	v_lshlrev_b32_e32 v214, 16, v91
	v_and_b32_e32 v215, 0xffff0000, v91
	v_pk_fma_f32 v[158:159], v[2:3], v[214:215], v[158:159]
	v_lshlrev_b32_e32 v94, 16, v92
	v_and_b32_e32 v95, 0xffff0000, v92
	v_pk_fma_f32 v[154:155], v[4:5], v[94:95], v[154:155]
	v_lshlrev_b32_e32 v214, 16, v93
	v_and_b32_e32 v215, 0xffff0000, v93
	v_pk_fma_f32 v[150:151], v[6:7], v[214:215], v[150:151]
	s_waitcnt vmcnt(0)
	v_lshlrev_b32_e32 v94, 16, v250
	v_and_b32_e32 v95, 0xffff0000, v250
	v_pk_fma_f32 v[146:147], v[8:9], v[94:95], v[146:147]
	v_lshlrev_b32_e32 v214, 16, v251
	v_and_b32_e32 v215, 0xffff0000, v251
	v_pk_fma_f32 v[144:145], v[10:11], v[214:215], v[144:145]
	v_lshlrev_b32_e32 v94, 16, v252
	v_and_b32_e32 v95, 0xffff0000, v252
	v_pk_fma_f32 v[142:143], v[12:13], v[94:95], v[142:143]
	v_lshlrev_b32_e32 v214, 16, v253
	v_and_b32_e32 v215, 0xffff0000, v253
	v_pk_fma_f32 v[140:141], v[14:15], v[214:215], v[140:141]
	v_mov_b32_e32 v0, 0
	v_mov_b32_e32 v1, v0
	v_mov_b32_e32 v2, v0
	v_mov_b32_e32 v3, v0
	v_mov_b32_e32 v4, v0
	v_mov_b32_e32 v5, v0
	v_mov_b32_e32 v6, v0
	v_mov_b32_e32 v7, v0
	v_mov_b32_e32 v8, v0
	v_mov_b32_e32 v9, v0
	v_mov_b32_e32 v10, v0
	v_mov_b32_e32 v11, v0
	v_mov_b32_e32 v12, v0
	v_mov_b32_e32 v13, v0
	v_mov_b32_e32 v14, v0
	v_mov_b32_e32 v15, v0
	v_mov_b32_e32 v16, v0
	v_mov_b32_e32 v17, v0
	v_mov_b32_e32 v18, v0
	v_mov_b32_e32 v19, v0
	v_mov_b32_e32 v20, v0
	v_mov_b32_e32 v21, v0
	v_mov_b32_e32 v22, v0
	v_mov_b32_e32 v23, v0
	v_mov_b32_e32 v24, v0
	v_mov_b32_e32 v25, v0
	v_mov_b32_e32 v26, v0
	v_mov_b32_e32 v27, v0
	v_mov_b32_e32 v28, v0
	v_mov_b32_e32 v29, v0
	v_mov_b32_e32 v30, v0
	v_mov_b32_e32 v31, v0
	v_mov_b32_e32 v32, v0
	v_mov_b32_e32 v33, v0
	v_mov_b32_e32 v34, v0
	v_mov_b32_e32 v35, v0
	v_mov_b32_e32 v36, v0
	v_mov_b32_e32 v37, v0
	v_mov_b32_e32 v38, v0
	v_mov_b32_e32 v39, v0
	v_mov_b32_e32 v40, v0
	v_mov_b32_e32 v41, v0
	v_mov_b32_e32 v42, v0
	v_mov_b32_e32 v43, v0
	v_mov_b32_e32 v44, v0
	v_mov_b32_e32 v45, v0
	v_mov_b32_e32 v46, v0
	v_mov_b32_e32 v47, v0
	v_mov_b32_e32 v48, v0
	v_mov_b32_e32 v49, v0
	v_mov_b32_e32 v50, v0
	v_mov_b32_e32 v51, v0
	v_mov_b32_e32 v52, v0
	v_mov_b32_e32 v53, v0
	v_mov_b32_e32 v54, v0
	v_mov_b32_e32 v55, v0
	v_mov_b32_e32 v56, v0
	v_mov_b32_e32 v57, v0
	v_mov_b32_e32 v58, v0
	v_mov_b32_e32 v59, v0
	v_mov_b32_e32 v60, v0
	v_mov_b32_e32 v61, v0
	v_mov_b32_e32 v62, v0
	v_mov_b32_e32 v63, v0
	s_branch .LBB0_189
